# v8 plus: duplicate s_waitcnt lgkmcnt(0) at each MFMA group front removed
# baseline (speedup 1.0000x reference)
; #define PG8_STAGE(bufoff, gbase, voff) do { _Pragma("unroll") for (int _i = 0; _i < 2; ++_i) \
;         __builtin_amdgcn_global_load_lds((const unsigned*)((const char*)(gbase) + (voff)[_i]), (LAS unsigned*)(lds + (bufoff) + ldsw + _i * 8192), 16, 0, 0); } while (0)
; #define PG8_LDA(dst, b, h) do { _Pragma("unroll") for (int m = 0; m < 4; ++m) _Pragma("unroll") for (int k = 0; k < 2; ++k) dst[m][k] = *(const LAS bf16x8*)(lds + PG8_SA(b, h) + aoff + m * 2048 + k * 1024); } while (0)
; #define PG8_LDB(dst, b, h) do { _Pragma("unroll") for (int n = 0; n < 2; ++n) _Pragma("unroll") for (int k = 0; k < 2; ++k) dst[n][k] = *(const LAS bf16x8*)(lds + PG8_SB(b, h) + boff + n * 2048 + k * 1024); } while (0)
; #define PG8_MMA(ai, bj, At, Bt) do { __builtin_amdgcn_s_setprio(1); _Pragma("unroll") for (int m = 0; m < 4; ++m) _Pragma("unroll") for (int n = 0; n < 2; ++n) _Pragma("unroll") for (int k = 0; k < 2; ++k) \
;         acc[ai][bj][m][n] = __builtin_amdgcn_mfma_f32_16x16x32_bf16(Bt[n][k], At[m][k], acc[ai][bj][m][n], 0, 0, 0); __builtin_amdgcn_s_setprio(0); } while (0)
; #define PG8_WAIT_V(n) asm volatile("s_waitcnt vmcnt(" #n ")" ::: "memory")
; #define PG8_WAIT_L(n) asm volatile("s_waitcnt lgkmcnt(" #n ")" ::: "memory")
; template <class Epi, class Sched>
; __device__ __forceinline__ void gemm_phase(LAS unsigned char* lds, const Gemm g, const Sched& S, const Epi& E) {
;     ...
;         for (int t = 0; t < nt; t += 2) {
;             const bool last = (t == nt - 2);
;             const char* a1 = cA + (size_t)(t + 1) * kstep;
;             const char* a2 = last ? nA : cA + (size_t)(t + 2) * kstep; const char* b2 = last ? nB : cB + (size_t)(t + 2) * kstep;
;             const char* a3 = a2 + kstep; const char* b3 = b2 + kstep;
;             PG8_LDB(B0, 0, 0); PG8_SCHED; PG8_LDA(At, 0, 0); PG8_STAGE(PG8_SA(1, 1), a1 + hstep, voffA);
;             PG8_WAIT_L(8); PG8_BAR; PG8_WAIT_L(0); PG8_MMA(0, 0, At, B0); PG8_BAR; PG8_SCHED;
;             PG8_LDB(B1, 0, 1); PG8_STAGE(PG8_SB(0, 0), b2, voffB);
;             PG8_BAR; PG8_WAIT_L(0); PG8_MMA(0, 1, At, B1); PG8_BAR;
;             PG8_LDA(At, 0, 1); PG8_STAGE(PG8_SA(0, 0), a2, voffA);
;             PG8_BAR; PG8_WAIT_L(0); PG8_MMA(1, 0, At, B0); PG8_BAR; PG8_SCHED;
;             PG8_STAGE(PG8_SB(0, 1), b2 + hstep, voffB);
;             PG8_WAIT_V(6); PG8_BAR; PG8_MMA(1, 1, At, B1); PG8_BAR;
.LBB0_165:
	s_add_u32 s24, s38, 0xfffc0080
	s_addc_u32 s25, s39, -1
	s_add_i32 vcc_hi, 0, 0x10000
	v_add_u32_e32 v166, vcc_hi, v167
	s_cmp_eq_u32 s50, 12
	s_cselect_b32 s61, s34, s25
	s_cselect_b32 s60, s45, s24
	s_cselect_b32 s49, s43, s35
	s_cselect_b32 s48, s79, vcc_lo
	v_lshl_add_u64 v[222:223], s[38:39], 0, v[140:141]
	s_add_i32 m0, s93, 0xc000
	ds_read_b128 v[214:217], v169 offset:6144
	ds_read_b128 v[218:221], v169 offset:7168
	global_load_lds_dwordx4 v[222:223], off
	v_lshl_add_u64 v[250:251], s[38:39], 0, v[138:139]
	s_add_i32 m0, s93, 0xe000
	s_nop 0
	global_load_lds_dwordx4 v[250:251], off
	s_waitcnt lgkmcnt(8)
	s_barrier
	s_waitcnt lgkmcnt(0)
	s_setprio 1
	v_mfma_f32_16x16x32_bf16 v[126:129], v[142:145], v[190:193], v[126:129]
	v_mfma_f32_16x16x32_bf16 v[126:129], v[162:165], v[194:197], v[126:129]
	v_mfma_f32_16x16x32_bf16 v[122:125], v[182:185], v[190:193], v[122:125]
	v_mfma_f32_16x16x32_bf16 v[122:125], v[186:189], v[194:197], v[122:125]
	v_mfma_f32_16x16x32_bf16 v[110:113], v[142:145], v[198:201], v[110:113]
	v_mfma_f32_16x16x32_bf16 v[110:113], v[162:165], v[202:205], v[110:113]
	v_mfma_f32_16x16x32_bf16 v[106:109], v[182:185], v[198:201], v[106:109]
	v_mfma_f32_16x16x32_bf16 v[106:109], v[186:189], v[202:205], v[106:109]
	v_mfma_f32_16x16x32_bf16 v[94:97], v[142:145], v[206:209], v[94:97]
	v_mfma_f32_16x16x32_bf16 v[94:97], v[162:165], v[210:213], v[94:97]
	v_mfma_f32_16x16x32_bf16 v[90:93], v[182:185], v[206:209], v[90:93]
	v_mfma_f32_16x16x32_bf16 v[90:93], v[186:189], v[210:213], v[90:93]
	v_mfma_f32_16x16x32_bf16 v[78:81], v[142:145], v[214:217], v[78:81]
	v_mfma_f32_16x16x32_bf16 v[78:81], v[162:165], v[218:221], v[78:81]
	v_mfma_f32_16x16x32_bf16 v[74:77], v[182:185], v[214:217], v[74:77]
	s_barrier
	v_mfma_f32_16x16x32_bf16 v[74:77], v[186:189], v[218:221], v[74:77]
	s_setprio 0
	s_add_i32 s51, 0, 0x14000
	s_add_i32 s24, vcc_hi, s86
	v_add_u32_e32 v166, s51, v167
	v_lshl_add_u64 v[238:239], s[48:49], 0, v[134:135]
	s_mov_b32 m0, s24
	ds_read_b128 v[222:225], v166
	ds_read_b128 v[226:229], v166 offset:1024
	ds_read_b128 v[230:233], v166 offset:2048
	ds_read_b128 v[234:237], v166 offset:3072
	global_load_lds_dwordx4 v[238:239], off
	v_lshl_add_u64 v[240:241], s[48:49], 0, v[130:131]
	s_add_i32 m0, s24, 0x2000
	s_nop 0
	global_load_lds_dwordx4 v[240:241], off
	s_barrier
	s_waitcnt lgkmcnt(0)
	s_setprio 1
	v_mfma_f32_16x16x32_bf16 v[118:121], v[222:225], v[190:193], v[118:121]
	v_mfma_f32_16x16x32_bf16 v[118:121], v[226:229], v[194:197], v[118:121]
	v_mfma_f32_16x16x32_bf16 v[114:117], v[230:233], v[190:193], v[114:117]
	v_mfma_f32_16x16x32_bf16 v[114:117], v[234:237], v[194:197], v[114:117]
	v_mfma_f32_16x16x32_bf16 v[102:105], v[222:225], v[198:201], v[102:105]
	v_mfma_f32_16x16x32_bf16 v[102:105], v[226:229], v[202:205], v[102:105]
	v_mfma_f32_16x16x32_bf16 v[98:101], v[230:233], v[198:201], v[98:101]
	v_mfma_f32_16x16x32_bf16 v[98:101], v[234:237], v[202:205], v[98:101]
	v_mfma_f32_16x16x32_bf16 v[86:89], v[222:225], v[206:209], v[86:89]
	v_mfma_f32_16x16x32_bf16 v[86:89], v[226:229], v[210:213], v[86:89]
	v_mfma_f32_16x16x32_bf16 v[82:85], v[230:233], v[206:209], v[82:85]
	v_mfma_f32_16x16x32_bf16 v[82:85], v[234:237], v[210:213], v[82:85]
	v_mfma_f32_16x16x32_bf16 v[70:73], v[222:225], v[214:217], v[70:73]
	v_mfma_f32_16x16x32_bf16 v[70:73], v[226:229], v[218:221], v[70:73]
	v_mfma_f32_16x16x32_bf16 v[66:69], v[230:233], v[214:217], v[66:69]
	s_barrier
	v_mfma_f32_16x16x32_bf16 v[66:69], v[234:237], v[218:221], v[66:69]
	s_setprio 0
	s_mov_b32 m0, s93
	v_lshl_add_u64 v[242:243], s[60:61], 0, v[136:137]
	ds_read_b128 v[190:193], v169 offset:16384
	ds_read_b128 v[194:197], v169 offset:17408
	ds_read_b128 v[198:201], v169 offset:18432
	ds_read_b128 v[202:205], v169 offset:19456
	ds_read_b128 v[206:209], v169 offset:20480
	ds_read_b128 v[210:213], v169 offset:21504
	ds_read_b128 v[214:217], v169 offset:22528
	ds_read_b128 v[218:221], v169 offset:23552
	global_load_lds_dwordx4 v[242:243], off
	v_lshl_add_u64 v[244:245], s[60:61], 0, v[132:133]
	s_mov_b32 m0, s98
	s_nop 0
	global_load_lds_dwordx4 v[244:245], off
	s_waitcnt vmcnt(8)
	s_barrier
	s_waitcnt lgkmcnt(0)
	s_setprio 1
	v_mfma_f32_16x16x32_bf16 v[62:65], v[142:145], v[190:193], v[62:65]
	v_mfma_f32_16x16x32_bf16 v[62:65], v[162:165], v[194:197], v[62:65]
	v_mfma_f32_16x16x32_bf16 v[58:61], v[182:185], v[190:193], v[58:61]
	v_mfma_f32_16x16x32_bf16 v[58:61], v[186:189], v[194:197], v[58:61]
	v_mfma_f32_16x16x32_bf16 v[46:49], v[142:145], v[198:201], v[46:49]
	v_mfma_f32_16x16x32_bf16 v[46:49], v[162:165], v[202:205], v[46:49]
	v_mfma_f32_16x16x32_bf16 v[42:45], v[182:185], v[198:201], v[42:45]
	v_mfma_f32_16x16x32_bf16 v[42:45], v[186:189], v[202:205], v[42:45]
	v_mfma_f32_16x16x32_bf16 v[30:33], v[142:145], v[206:209], v[30:33]
	v_mfma_f32_16x16x32_bf16 v[30:33], v[162:165], v[210:213], v[30:33]
	v_mfma_f32_16x16x32_bf16 v[26:29], v[182:185], v[206:209], v[26:29]
	v_mfma_f32_16x16x32_bf16 v[26:29], v[186:189], v[210:213], v[26:29]
	v_mfma_f32_16x16x32_bf16 v[14:17], v[142:145], v[214:217], v[14:17]
	v_mfma_f32_16x16x32_bf16 v[14:17], v[162:165], v[218:221], v[14:17]
	v_mfma_f32_16x16x32_bf16 v[10:13], v[182:185], v[214:217], v[10:13]
	s_barrier
	v_mfma_f32_16x16x32_bf16 v[10:13], v[186:189], v[218:221], v[10:13]
	s_setprio 0
	s_add_u32 s24, s48, 0x40000
	s_addc_u32 s25, s49, 0
	s_add_i32 s51, s51, s86
	v_lshl_add_u64 v[142:143], s[24:25], 0, v[134:135]
	s_mov_b32 m0, s51
	s_nop 0
	global_load_lds_dwordx4 v[142:143], off
	v_lshl_add_u64 v[250:251], s[24:25], 0, v[130:131]
	s_add_i32 m0, s51, 0x2000
	s_nop 0
	global_load_lds_dwordx4 v[250:251], off
	s_waitcnt vmcnt(6)
	v_add_u32_e32 v249, 0x18000, v167
	s_barrier
; #define PG8_STAGE(bufoff, gbase, voff) do { _Pragma("unroll") for (int _i = 0; _i < 2; ++_i) \
;         __builtin_amdgcn_global_load_lds((const unsigned*)((const char*)(gbase) + (voff)[_i]), (LAS unsigned*)(lds + (bufoff) + ldsw + _i * 8192), 16, 0, 0); } while (0)
; #define PG8_LDA(dst, b, h) do { _Pragma("unroll") for (int m = 0; m < 4; ++m) _Pragma("unroll") for (int k = 0; k < 2; ++k) dst[m][k] = *(const LAS bf16x8*)(lds + PG8_SA(b, h) + aoff + m * 2048 + k * 1024); } while (0)
; #define PG8_LDB(dst, b, h) do { _Pragma("unroll") for (int n = 0; n < 2; ++n) _Pragma("unroll") for (int k = 0; k < 2; ++k) dst[n][k] = *(const LAS bf16x8*)(lds + PG8_SB(b, h) + boff + n * 2048 + k * 1024); } while (0)
; #define PG8_MMA(ai, bj, At, Bt) do { __builtin_amdgcn_s_setprio(1); _Pragma("unroll") for (int m = 0; m < 4; ++m) _Pragma("unroll") for (int n = 0; n < 2; ++n) _Pragma("unroll") for (int k = 0; k < 2; ++k) \
;         acc[ai][bj][m][n] = __builtin_amdgcn_mfma_f32_16x16x32_bf16(Bt[n][k], At[m][k], acc[ai][bj][m][n], 0, 0, 0); __builtin_amdgcn_s_setprio(0); } while (0)
; #define PG8_WAIT_V(n) asm volatile("s_waitcnt vmcnt(" #n ")" ::: "memory")
; #define PG8_WAIT_L(n) asm volatile("s_waitcnt lgkmcnt(" #n ")" ::: "memory")
; #define PG8_BAR __builtin_amdgcn_s_barrier()
; #define PG8_SCHED __builtin_amdgcn_sched_barrier(0)
; template <class Epi, class Sched>
; __device__ __forceinline__ void gemm_phase(LAS unsigned char* lds, const Gemm g, const Sched& S, const Epi& E) {
;     ...
;             PG8_WAIT_V(6); PG8_BAR; PG8_MMA(1, 1, At, B1); PG8_BAR;
;             PG8_LDB(B0, 1, 0); PG8_SCHED; PG8_LDA(At, 1, 0); PG8_STAGE(PG8_SA(0, 1), a2 + hstep, voffA);
;             PG8_WAIT_L(8); PG8_BAR; PG8_WAIT_L(0); PG8_MMA(0, 0, At, B0); PG8_BAR; PG8_SCHED;
;             PG8_LDB(B1, 1, 1); PG8_STAGE(PG8_SB(1, 0), b3, voffB);
;             PG8_BAR; PG8_WAIT_L(0); PG8_MMA(0, 1, At, B1); PG8_BAR;
	s_setprio 1
	v_mfma_f32_16x16x32_bf16 v[54:57], v[222:225], v[190:193], v[54:57]
	ds_read_b128 v[142:145], v249
	ds_read_b128 v[162:165], v249 offset:1024
	v_mfma_f32_16x16x32_bf16 v[54:57], v[226:229], v[194:197], v[54:57]
	ds_read_b128 v[182:185], v249 offset:2048
	ds_read_b128 v[186:189], v249 offset:3072
	v_mfma_f32_16x16x32_bf16 v[50:53], v[230:233], v[190:193], v[50:53]
	ds_read_b128 v[190:193], v169 offset:32768
	v_mfma_f32_16x16x32_bf16 v[50:53], v[234:237], v[194:197], v[50:53]
	ds_read_b128 v[194:197], v169 offset:33792
	v_mfma_f32_16x16x32_bf16 v[38:41], v[222:225], v[198:201], v[38:41]
	v_mfma_f32_16x16x32_bf16 v[38:41], v[226:229], v[202:205], v[38:41]
	v_mfma_f32_16x16x32_bf16 v[34:37], v[230:233], v[198:201], v[34:37]
	ds_read_b128 v[198:201], v169 offset:34816
	v_mfma_f32_16x16x32_bf16 v[34:37], v[234:237], v[202:205], v[34:37]
	ds_read_b128 v[202:205], v169 offset:35840
	v_mfma_f32_16x16x32_bf16 v[22:25], v[222:225], v[206:209], v[22:25]
	v_mfma_f32_16x16x32_bf16 v[22:25], v[226:229], v[210:213], v[22:25]
	v_mfma_f32_16x16x32_bf16 v[18:21], v[230:233], v[206:209], v[18:21]
	ds_read_b128 v[206:209], v169 offset:36864
	v_mfma_f32_16x16x32_bf16 v[18:21], v[234:237], v[210:213], v[18:21]
	ds_read_b128 v[210:213], v169 offset:37888
	v_mfma_f32_16x16x32_bf16 v[6:9], v[222:225], v[214:217], v[6:9]
	v_mfma_f32_16x16x32_bf16 v[6:9], v[226:229], v[218:221], v[6:9]
	v_mfma_f32_16x16x32_bf16 v[2:5], v[230:233], v[214:217], v[2:5]
	s_barrier
	v_mfma_f32_16x16x32_bf16 v[2:5], v[234:237], v[218:221], v[2:5]
	s_setprio 0
	s_add_i32 s51, 0, 0x18000
	v_add_u32_e32 v166, s51, v167
	s_add_u32 s24, s60, 0x40000
	s_addc_u32 s25, s61, 0
	s_mov_b32 m0, s99
	v_lshl_add_u64 v[222:223], s[24:25], 0, v[136:137]
	ds_read_b128 v[214:217], v169 offset:38912
	ds_read_b128 v[218:221], v169 offset:39936
	global_load_lds_dwordx4 v[222:223], off
	v_lshl_add_u64 v[250:251], s[24:25], 0, v[132:133]
	s_mov_b32 m0, s94
	s_nop 0
	global_load_lds_dwordx4 v[250:251], off
	s_waitcnt lgkmcnt(8)
	s_barrier
	s_waitcnt lgkmcnt(0)
	s_setprio 1
	v_mfma_f32_16x16x32_bf16 v[126:129], v[142:145], v[190:193], v[126:129]
	v_mfma_f32_16x16x32_bf16 v[126:129], v[162:165], v[194:197], v[126:129]
	v_mfma_f32_16x16x32_bf16 v[122:125], v[182:185], v[190:193], v[122:125]
	v_mfma_f32_16x16x32_bf16 v[122:125], v[186:189], v[194:197], v[122:125]
	v_mfma_f32_16x16x32_bf16 v[110:113], v[142:145], v[198:201], v[110:113]
	v_mfma_f32_16x16x32_bf16 v[110:113], v[162:165], v[202:205], v[110:113]
	v_mfma_f32_16x16x32_bf16 v[106:109], v[182:185], v[198:201], v[106:109]
	v_mfma_f32_16x16x32_bf16 v[106:109], v[186:189], v[202:205], v[106:109]
	v_mfma_f32_16x16x32_bf16 v[94:97], v[142:145], v[206:209], v[94:97]
	v_mfma_f32_16x16x32_bf16 v[94:97], v[162:165], v[210:213], v[94:97]
	v_mfma_f32_16x16x32_bf16 v[90:93], v[182:185], v[206:209], v[90:93]
	v_mfma_f32_16x16x32_bf16 v[90:93], v[186:189], v[210:213], v[90:93]
	v_mfma_f32_16x16x32_bf16 v[78:81], v[142:145], v[214:217], v[78:81]
	v_mfma_f32_16x16x32_bf16 v[78:81], v[162:165], v[218:221], v[78:81]
	v_mfma_f32_16x16x32_bf16 v[74:77], v[182:185], v[214:217], v[74:77]
	s_barrier
	v_mfma_f32_16x16x32_bf16 v[74:77], v[186:189], v[218:221], v[74:77]
	s_setprio 0
	s_add_i32 s60, 0, 0x1c000
	s_add_i32 s24, s51, s86
	v_add_u32_e32 v166, s60, v167
	v_lshl_add_u64 v[238:239], v[238:239], 0, s[12:13]
	s_mov_b32 m0, s24
	ds_read_b128 v[222:225], v166
	ds_read_b128 v[226:229], v166 offset:1024
	ds_read_b128 v[230:233], v166 offset:2048
	ds_read_b128 v[234:237], v166 offset:3072
	global_load_lds_dwordx4 v[238:239], off
	v_lshl_add_u64 v[250:251], v[240:241], 0, s[12:13]
	s_add_i32 m0, s24, 0x2000
	s_nop 0
	global_load_lds_dwordx4 v[250:251], off
	s_barrier
	s_waitcnt lgkmcnt(0)
	s_setprio 1
	v_mfma_f32_16x16x32_bf16 v[118:121], v[222:225], v[190:193], v[118:121]
	v_mfma_f32_16x16x32_bf16 v[118:121], v[226:229], v[194:197], v[118:121]
	v_mfma_f32_16x16x32_bf16 v[114:117], v[230:233], v[190:193], v[114:117]
	v_mfma_f32_16x16x32_bf16 v[114:117], v[234:237], v[194:197], v[114:117]
	v_mfma_f32_16x16x32_bf16 v[102:105], v[222:225], v[198:201], v[102:105]
	v_mfma_f32_16x16x32_bf16 v[102:105], v[226:229], v[202:205], v[102:105]
	v_mfma_f32_16x16x32_bf16 v[98:101], v[230:233], v[198:201], v[98:101]
	v_mfma_f32_16x16x32_bf16 v[98:101], v[234:237], v[202:205], v[98:101]
	v_mfma_f32_16x16x32_bf16 v[86:89], v[222:225], v[206:209], v[86:89]
	v_mfma_f32_16x16x32_bf16 v[86:89], v[226:229], v[210:213], v[86:89]
	v_mfma_f32_16x16x32_bf16 v[82:85], v[230:233], v[206:209], v[82:85]
	v_mfma_f32_16x16x32_bf16 v[82:85], v[234:237], v[210:213], v[82:85]
	v_mfma_f32_16x16x32_bf16 v[70:73], v[222:225], v[214:217], v[70:73]
	v_mfma_f32_16x16x32_bf16 v[70:73], v[226:229], v[218:221], v[70:73]
	v_mfma_f32_16x16x32_bf16 v[66:69], v[230:233], v[214:217], v[66:69]
	s_barrier
; #define PG8_STAGE(bufoff, gbase, voff) do { _Pragma("unroll") for (int _i = 0; _i < 2; ++_i) \
;         __builtin_amdgcn_global_load_lds((const unsigned*)((const char*)(gbase) + (voff)[_i]), (LAS unsigned*)(lds + (bufoff) + ldsw + _i * 8192), 16, 0, 0); } while (0)
; #define PG8_LDA(dst, b, h) do { _Pragma("unroll") for (int m = 0; m < 4; ++m) _Pragma("unroll") for (int k = 0; k < 2; ++k) dst[m][k] = *(const LAS bf16x8*)(lds + PG8_SA(b, h) + aoff + m * 2048 + k * 1024); } while (0)
; #define PG8_MMA(ai, bj, At, Bt) do { __builtin_amdgcn_s_setprio(1); _Pragma("unroll") for (int m = 0; m < 4; ++m) _Pragma("unroll") for (int n = 0; n < 2; ++n) _Pragma("unroll") for (int k = 0; k < 2; ++k) \
;         acc[ai][bj][m][n] = __builtin_amdgcn_mfma_f32_16x16x32_bf16(Bt[n][k], At[m][k], acc[ai][bj][m][n], 0, 0, 0); __builtin_amdgcn_s_setprio(0); } while (0)
; #define PG8_WAIT_V(n) asm volatile("s_waitcnt vmcnt(" #n ")" ::: "memory")
; #define PG8_WAIT_L(n) asm volatile("s_waitcnt lgkmcnt(" #n ")" ::: "memory")
; #define PG8_BAR __builtin_amdgcn_s_barrier()
; #define PG8_SCHED __builtin_amdgcn_sched_barrier(0)
; template <class Epi, class Sched>
; __device__ __forceinline__ void gemm_phase(LAS unsigned char* lds, const Gemm g, const Sched& S, const Epi& E) {
;     ...
;             PG8_LDA(At, 1, 1); PG8_STAGE(PG8_SA(1, 0), a3, voffA);
;             PG8_BAR; PG8_WAIT_L(0); PG8_MMA(1, 0, At, B0); PG8_BAR; PG8_SCHED;
;             PG8_STAGE(PG8_SB(1, 1), b3 + hstep, voffB);
;             PG8_WAIT_V(6); PG8_BAR; PG8_MMA(1, 1, At, B1); PG8_BAR;
;         }
;         if (wr == 0) PG8_BAR;
	v_mfma_f32_16x16x32_bf16 v[66:69], v[234:237], v[218:221], v[66:69]
	s_setprio 0
	s_mov_b32 m0, s95
	v_lshl_add_u64 v[238:239], v[242:243], 0, s[12:13]
	ds_read_b128 v[190:193], v169 offset:49152
	ds_read_b128 v[194:197], v169 offset:50176
	ds_read_b128 v[198:201], v169 offset:51200
	ds_read_b128 v[202:205], v169 offset:52224
	ds_read_b128 v[206:209], v169 offset:53248
	ds_read_b128 v[210:213], v169 offset:54272
	ds_read_b128 v[214:217], v169 offset:55296
	ds_read_b128 v[218:221], v169 offset:56320
	global_load_lds_dwordx4 v[238:239], off
	v_lshl_add_u64 v[250:251], v[244:245], 0, s[12:13]
	s_mov_b32 m0, s96
	s_nop 0
	global_load_lds_dwordx4 v[250:251], off
	s_waitcnt vmcnt(8)
	s_barrier
	s_waitcnt lgkmcnt(0)
	s_setprio 1
	v_mfma_f32_16x16x32_bf16 v[62:65], v[142:145], v[190:193], v[62:65]
	v_mfma_f32_16x16x32_bf16 v[62:65], v[162:165], v[194:197], v[62:65]
	v_mfma_f32_16x16x32_bf16 v[58:61], v[182:185], v[190:193], v[58:61]
	v_mfma_f32_16x16x32_bf16 v[58:61], v[186:189], v[194:197], v[58:61]
	v_mfma_f32_16x16x32_bf16 v[46:49], v[142:145], v[198:201], v[46:49]
	v_mfma_f32_16x16x32_bf16 v[46:49], v[162:165], v[202:205], v[46:49]
	v_mfma_f32_16x16x32_bf16 v[42:45], v[182:185], v[198:201], v[42:45]
	v_mfma_f32_16x16x32_bf16 v[42:45], v[186:189], v[202:205], v[42:45]
	v_mfma_f32_16x16x32_bf16 v[30:33], v[142:145], v[206:209], v[30:33]
	v_mfma_f32_16x16x32_bf16 v[30:33], v[162:165], v[210:213], v[30:33]
	v_mfma_f32_16x16x32_bf16 v[26:29], v[182:185], v[206:209], v[26:29]
	v_mfma_f32_16x16x32_bf16 v[26:29], v[186:189], v[210:213], v[26:29]
	v_mfma_f32_16x16x32_bf16 v[14:17], v[142:145], v[214:217], v[14:17]
	v_mfma_f32_16x16x32_bf16 v[14:17], v[162:165], v[218:221], v[14:17]
	v_mfma_f32_16x16x32_bf16 v[10:13], v[182:185], v[214:217], v[10:13]
	s_barrier
	v_mfma_f32_16x16x32_bf16 v[10:13], v[186:189], v[218:221], v[10:13]
	s_setprio 0
	s_add_u32 s24, s48, 0x40080
	s_addc_u32 s25, s49, 0
	s_add_i32 s48, s60, s86
	v_lshl_add_u64 v[142:143], s[24:25], 0, v[134:135]
	s_mov_b32 m0, s48
	s_nop 0
	global_load_lds_dwordx4 v[142:143], off
	v_lshl_add_u64 v[250:251], s[24:25], 0, v[130:131]
	s_add_i32 m0, s48, 0x2000
	s_nop 0
	global_load_lds_dwordx4 v[250:251], off
	s_waitcnt vmcnt(6)
	v_add_u32_e32 v249, 0x10000, v167
	s_barrier
	s_setprio 1
	v_mfma_f32_16x16x32_bf16 v[54:57], v[222:225], v[190:193], v[54:57]
	ds_read_b128 v[142:145], v249
	ds_read_b128 v[162:165], v249 offset:1024
	v_mfma_f32_16x16x32_bf16 v[54:57], v[226:229], v[194:197], v[54:57]
	ds_read_b128 v[182:185], v249 offset:2048
	ds_read_b128 v[186:189], v249 offset:3072
	v_mfma_f32_16x16x32_bf16 v[50:53], v[230:233], v[190:193], v[50:53]
	ds_read_b128 v[190:193], v169
	v_mfma_f32_16x16x32_bf16 v[50:53], v[234:237], v[194:197], v[50:53]
	ds_read_b128 v[194:197], v169 offset:1024
	v_mfma_f32_16x16x32_bf16 v[38:41], v[222:225], v[198:201], v[38:41]
	v_mfma_f32_16x16x32_bf16 v[38:41], v[226:229], v[202:205], v[38:41]
	v_mfma_f32_16x16x32_bf16 v[34:37], v[230:233], v[198:201], v[34:37]
	ds_read_b128 v[198:201], v169 offset:2048
	v_mfma_f32_16x16x32_bf16 v[34:37], v[234:237], v[202:205], v[34:37]
	ds_read_b128 v[202:205], v169 offset:3072
	v_mfma_f32_16x16x32_bf16 v[22:25], v[222:225], v[206:209], v[22:25]
	v_mfma_f32_16x16x32_bf16 v[22:25], v[226:229], v[210:213], v[22:25]
	v_mfma_f32_16x16x32_bf16 v[18:21], v[230:233], v[206:209], v[18:21]
	ds_read_b128 v[206:209], v169 offset:4096
	v_mfma_f32_16x16x32_bf16 v[18:21], v[234:237], v[210:213], v[18:21]
	ds_read_b128 v[210:213], v169 offset:5120
	v_mfma_f32_16x16x32_bf16 v[6:9], v[222:225], v[214:217], v[6:9]
	v_mfma_f32_16x16x32_bf16 v[6:9], v[226:229], v[218:221], v[6:9]
	v_mfma_f32_16x16x32_bf16 v[2:5], v[230:233], v[214:217], v[2:5]
	s_barrier
	v_mfma_f32_16x16x32_bf16 v[2:5], v[234:237], v[218:221], v[2:5]
	s_setprio 0
	s_add_i32 s50, s50, 2
	s_add_u32 vcc_lo, vcc_lo, 0x100
	s_addc_u32 s35, s35, 0
	s_add_u32 s38, s38, 0x100
	s_addc_u32 s39, s39, 0
	s_cmp_gt_u32 s50, 13
	s_cbranch_scc0 .LBB0_165
	s_waitcnt lgkmcnt(0)
	s_and_b64 vcc, exec, s[40:41]
	s_cbranch_vccz .LBB0_168
	s_barrier

; #define PG8_STAGE(bufoff, gbase, voff) do { _Pragma("unroll") for (int _i = 0; _i < 2; ++_i) \
;         __builtin_amdgcn_global_load_lds((const unsigned*)((const char*)(gbase) + (voff)[_i]), (LAS unsigned*)(lds + (bufoff) + ldsw + _i * 8192), 16, 0, 0); } while (0)
; #define PG8_LDA(dst, b, h) do { _Pragma("unroll") for (int m = 0; m < 4; ++m) _Pragma("unroll") for (int k = 0; k < 2; ++k) dst[m][k] = *(const LAS bf16x8*)(lds + PG8_SA(b, h) + aoff + m * 2048 + k * 1024); } while (0)
; #define PG8_LDB(dst, b, h) do { _Pragma("unroll") for (int n = 0; n < 2; ++n) _Pragma("unroll") for (int k = 0; k < 2; ++k) dst[n][k] = *(const LAS bf16x8*)(lds + PG8_SB(b, h) + boff + n * 2048 + k * 1024); } while (0)
; #define PG8_MMA(ai, bj, At, Bt) do { __builtin_amdgcn_s_setprio(1); _Pragma("unroll") for (int m = 0; m < 4; ++m) _Pragma("unroll") for (int n = 0; n < 2; ++n) _Pragma("unroll") for (int k = 0; k < 2; ++k) \
;         acc[ai][bj][m][n] = __builtin_amdgcn_mfma_f32_16x16x32_bf16(Bt[n][k], At[m][k], acc[ai][bj][m][n], 0, 0, 0); __builtin_amdgcn_s_setprio(0); } while (0)
; #define PG8_WAIT_V(n) asm volatile("s_waitcnt vmcnt(" #n ")" ::: "memory")
; #define PG8_WAIT_L(n) asm volatile("s_waitcnt lgkmcnt(" #n ")" ::: "memory")
; template <class Epi, class Sched>
; __device__ __forceinline__ void gemm_phase(LAS unsigned char* lds, const Gemm g, const Sched& S, const Epi& E) {
;     ...
;         for (int t = 0; t < nt; t += 2) {
;             const bool last = (t == nt - 2);
;             const char* a1 = cA + (size_t)(t + 1) * kstep;
;             const char* a2 = last ? nA : cA + (size_t)(t + 2) * kstep; const char* b2 = last ? nB : cB + (size_t)(t + 2) * kstep;
;             const char* a3 = a2 + kstep; const char* b3 = b2 + kstep;
;             PG8_LDB(B0, 0, 0); PG8_SCHED; PG8_LDA(At, 0, 0); PG8_STAGE(PG8_SA(1, 1), a1 + hstep, voffA);
;             PG8_WAIT_L(8); PG8_BAR; PG8_WAIT_L(0); PG8_MMA(0, 0, At, B0); PG8_BAR; PG8_SCHED;
;             PG8_LDB(B1, 0, 1); PG8_STAGE(PG8_SB(0, 0), b2, voffB);
;             PG8_BAR; PG8_WAIT_L(0); PG8_MMA(0, 1, At, B1); PG8_BAR;
;             PG8_LDA(At, 0, 1); PG8_STAGE(PG8_SA(0, 0), a2, voffA);
;             PG8_BAR; PG8_WAIT_L(0); PG8_MMA(1, 0, At, B0); PG8_BAR; PG8_SCHED;
;             PG8_STAGE(PG8_SB(0, 1), b2 + hstep, voffB);
;             PG8_WAIT_V(6); PG8_BAR; PG8_MMA(1, 1, At, B1); PG8_BAR;
.LBB0_416:
	s_add_u32 s24, s0, 0xfffc0080
	s_addc_u32 s25, s1, -1
	s_add_i32 s39, 0, 0x10000
	v_add_u32_e32 v142, s39, v144
	s_cmp_eq_u32 s38, 12
	s_cselect_b32 vcc_hi, s77, s25
	s_cselect_b32 vcc_lo, s76, s24
	s_cselect_b32 s37, s47, s50
	s_cselect_b32 s36, s61, s35
	v_lshl_add_u64 v[142:143], s[0:1], 0, v[140:141]
	s_add_i32 m0, s93, 0xc000
	ds_read_b128 v[218:221], v162 offset:6144
	ds_read_b128 v[222:225], v162 offset:7168
	global_load_lds_dwordx4 v[142:143], off
	v_lshl_add_u64 v[250:251], s[0:1], 0, v[138:139]
	s_add_i32 m0, s93, 0xe000
	s_nop 0
	global_load_lds_dwordx4 v[250:251], off
	s_waitcnt lgkmcnt(8)
	s_barrier
	s_waitcnt lgkmcnt(0)
	s_setprio 1
	v_mfma_f32_16x16x32_bf16 v[126:129], v[164:167], v[194:197], v[126:129]
	v_mfma_f32_16x16x32_bf16 v[126:129], v[182:185], v[198:201], v[126:129]
	v_mfma_f32_16x16x32_bf16 v[122:125], v[186:189], v[194:197], v[122:125]
	v_mfma_f32_16x16x32_bf16 v[122:125], v[190:193], v[198:201], v[122:125]
	v_mfma_f32_16x16x32_bf16 v[118:121], v[164:167], v[202:205], v[118:121]
	v_mfma_f32_16x16x32_bf16 v[118:121], v[182:185], v[206:209], v[118:121]
	v_mfma_f32_16x16x32_bf16 v[110:113], v[186:189], v[202:205], v[110:113]
	v_mfma_f32_16x16x32_bf16 v[110:113], v[190:193], v[206:209], v[110:113]
	v_mfma_f32_16x16x32_bf16 v[102:105], v[164:167], v[210:213], v[102:105]
	v_mfma_f32_16x16x32_bf16 v[102:105], v[182:185], v[214:217], v[102:105]
	v_mfma_f32_16x16x32_bf16 v[94:97], v[186:189], v[210:213], v[94:97]
	v_mfma_f32_16x16x32_bf16 v[94:97], v[190:193], v[214:217], v[94:97]
	v_mfma_f32_16x16x32_bf16 v[86:89], v[164:167], v[218:221], v[86:89]
	v_mfma_f32_16x16x32_bf16 v[86:89], v[182:185], v[222:225], v[86:89]
	v_mfma_f32_16x16x32_bf16 v[78:81], v[186:189], v[218:221], v[78:81]
	s_barrier
	v_mfma_f32_16x16x32_bf16 v[78:81], v[190:193], v[222:225], v[78:81]
	s_setprio 0
	s_add_i32 s51, 0, 0x14000
	v_add_u32_e32 v142, s51, v144
	s_add_i32 s24, s39, s86
	ds_read_b128 v[226:229], v142
	ds_read_b128 v[230:233], v142 offset:1024
	ds_read_b128 v[234:237], v142 offset:2048
	ds_read_b128 v[238:241], v142 offset:3072
	v_lshl_add_u64 v[142:143], s[36:37], 0, v[134:135]
	s_mov_b32 m0, s24
	v_lshl_add_u64 v[168:169], s[36:37], 0, v[130:131]
	global_load_lds_dwordx4 v[142:143], off
	s_add_i32 m0, s24, 0x2000
	s_nop 0
	global_load_lds_dwordx4 v[168:169], off
	s_barrier
	s_waitcnt lgkmcnt(0)
	s_setprio 1
	v_mfma_f32_16x16x32_bf16 v[114:117], v[226:229], v[194:197], v[114:117]
	v_mfma_f32_16x16x32_bf16 v[114:117], v[230:233], v[198:201], v[114:117]
	v_mfma_f32_16x16x32_bf16 v[106:109], v[234:237], v[194:197], v[106:109]
	v_mfma_f32_16x16x32_bf16 v[106:109], v[238:241], v[198:201], v[106:109]
	v_mfma_f32_16x16x32_bf16 v[98:101], v[226:229], v[202:205], v[98:101]
	v_mfma_f32_16x16x32_bf16 v[98:101], v[230:233], v[206:209], v[98:101]
	v_mfma_f32_16x16x32_bf16 v[90:93], v[234:237], v[202:205], v[90:93]
	v_mfma_f32_16x16x32_bf16 v[90:93], v[238:241], v[206:209], v[90:93]
	v_mfma_f32_16x16x32_bf16 v[82:85], v[226:229], v[210:213], v[82:85]
	v_mfma_f32_16x16x32_bf16 v[82:85], v[230:233], v[214:217], v[82:85]
	v_mfma_f32_16x16x32_bf16 v[74:77], v[234:237], v[210:213], v[74:77]
	v_mfma_f32_16x16x32_bf16 v[74:77], v[238:241], v[214:217], v[74:77]
	v_mfma_f32_16x16x32_bf16 v[70:73], v[226:229], v[218:221], v[70:73]
	v_mfma_f32_16x16x32_bf16 v[70:73], v[230:233], v[222:225], v[70:73]
	v_mfma_f32_16x16x32_bf16 v[66:69], v[234:237], v[218:221], v[66:69]
	s_barrier
	v_mfma_f32_16x16x32_bf16 v[66:69], v[238:241], v[222:225], v[66:69]
	s_setprio 0
	s_mov_b32 m0, s93
	v_lshl_add_u64 v[242:243], vcc, 0, v[136:137]
	ds_read_b128 v[194:197], v162 offset:16384
	ds_read_b128 v[198:201], v162 offset:17408
	ds_read_b128 v[202:205], v162 offset:18432
	ds_read_b128 v[206:209], v162 offset:19456
	ds_read_b128 v[210:213], v162 offset:20480
	ds_read_b128 v[214:217], v162 offset:21504
	ds_read_b128 v[218:221], v162 offset:22528
	ds_read_b128 v[222:225], v162 offset:23552
	global_load_lds_dwordx4 v[242:243], off
	v_lshl_add_u64 v[244:245], vcc, 0, v[132:133]
	s_mov_b32 m0, s94
	s_nop 0
	global_load_lds_dwordx4 v[244:245], off
	s_waitcnt vmcnt(8)
	s_barrier
	s_waitcnt lgkmcnt(0)
	s_setprio 1
	v_mfma_f32_16x16x32_bf16 v[62:65], v[164:167], v[194:197], v[62:65]
	v_mfma_f32_16x16x32_bf16 v[62:65], v[182:185], v[198:201], v[62:65]
	v_mfma_f32_16x16x32_bf16 v[58:61], v[186:189], v[194:197], v[58:61]
	v_mfma_f32_16x16x32_bf16 v[58:61], v[190:193], v[198:201], v[58:61]
	v_mfma_f32_16x16x32_bf16 v[54:57], v[164:167], v[202:205], v[54:57]
	v_mfma_f32_16x16x32_bf16 v[54:57], v[182:185], v[206:209], v[54:57]
	v_mfma_f32_16x16x32_bf16 v[46:49], v[186:189], v[202:205], v[46:49]
	v_mfma_f32_16x16x32_bf16 v[46:49], v[190:193], v[206:209], v[46:49]
	v_mfma_f32_16x16x32_bf16 v[38:41], v[164:167], v[210:213], v[38:41]
	v_mfma_f32_16x16x32_bf16 v[38:41], v[182:185], v[214:217], v[38:41]
	v_mfma_f32_16x16x32_bf16 v[30:33], v[186:189], v[210:213], v[30:33]
	v_mfma_f32_16x16x32_bf16 v[30:33], v[190:193], v[214:217], v[30:33]
	v_mfma_f32_16x16x32_bf16 v[22:25], v[164:167], v[218:221], v[22:25]
	v_mfma_f32_16x16x32_bf16 v[22:25], v[182:185], v[222:225], v[22:25]
	v_mfma_f32_16x16x32_bf16 v[14:17], v[186:189], v[218:221], v[14:17]
	s_barrier
	v_mfma_f32_16x16x32_bf16 v[14:17], v[190:193], v[222:225], v[14:17]
	s_setprio 0
	s_add_u32 s24, s36, 0x40000
	s_addc_u32 s25, s37, 0
	s_add_i32 s39, s51, s86
	v_lshl_add_u64 v[164:165], s[24:25], 0, v[134:135]
	s_mov_b32 m0, s39
	s_nop 0
	global_load_lds_dwordx4 v[164:165], off
	v_lshl_add_u64 v[250:251], s[24:25], 0, v[130:131]
	s_add_i32 m0, s39, 0x2000
	s_nop 0
	global_load_lds_dwordx4 v[250:251], off
	s_waitcnt vmcnt(6)
	v_add_u32_e32 v249, 0x18000, v144
	s_barrier
; #define PG8_STAGE(bufoff, gbase, voff) do { _Pragma("unroll") for (int _i = 0; _i < 2; ++_i) \
;         __builtin_amdgcn_global_load_lds((const unsigned*)((const char*)(gbase) + (voff)[_i]), (LAS unsigned*)(lds + (bufoff) + ldsw + _i * 8192), 16, 0, 0); } while (0)
; #define PG8_LDA(dst, b, h) do { _Pragma("unroll") for (int m = 0; m < 4; ++m) _Pragma("unroll") for (int k = 0; k < 2; ++k) dst[m][k] = *(const LAS bf16x8*)(lds + PG8_SA(b, h) + aoff + m * 2048 + k * 1024); } while (0)
; #define PG8_LDB(dst, b, h) do { _Pragma("unroll") for (int n = 0; n < 2; ++n) _Pragma("unroll") for (int k = 0; k < 2; ++k) dst[n][k] = *(const LAS bf16x8*)(lds + PG8_SB(b, h) + boff + n * 2048 + k * 1024); } while (0)
; #define PG8_MMA(ai, bj, At, Bt) do { __builtin_amdgcn_s_setprio(1); _Pragma("unroll") for (int m = 0; m < 4; ++m) _Pragma("unroll") for (int n = 0; n < 2; ++n) _Pragma("unroll") for (int k = 0; k < 2; ++k) \
;         acc[ai][bj][m][n] = __builtin_amdgcn_mfma_f32_16x16x32_bf16(Bt[n][k], At[m][k], acc[ai][bj][m][n], 0, 0, 0); __builtin_amdgcn_s_setprio(0); } while (0)
; #define PG8_WAIT_V(n) asm volatile("s_waitcnt vmcnt(" #n ")" ::: "memory")
; #define PG8_WAIT_L(n) asm volatile("s_waitcnt lgkmcnt(" #n ")" ::: "memory")
; #define PG8_BAR __builtin_amdgcn_s_barrier()
; #define PG8_SCHED __builtin_amdgcn_sched_barrier(0)
; template <class Epi, class Sched>
; __device__ __forceinline__ void gemm_phase(LAS unsigned char* lds, const Gemm g, const Sched& S, const Epi& E) {
;     ...
;             PG8_WAIT_V(6); PG8_BAR; PG8_MMA(1, 1, At, B1); PG8_BAR;
;             PG8_LDB(B0, 1, 0); PG8_SCHED; PG8_LDA(At, 1, 0); PG8_STAGE(PG8_SA(0, 1), a2 + hstep, voffA);
;             PG8_WAIT_L(8); PG8_BAR; PG8_WAIT_L(0); PG8_MMA(0, 0, At, B0); PG8_BAR; PG8_SCHED;
;             PG8_LDB(B1, 1, 1); PG8_STAGE(PG8_SB(1, 0), b3, voffB);
;             PG8_BAR; PG8_WAIT_L(0); PG8_MMA(0, 1, At, B1); PG8_BAR;
	s_setprio 1
	v_mfma_f32_16x16x32_bf16 v[50:53], v[226:229], v[194:197], v[50:53]
	ds_read_b128 v[164:167], v249
	ds_read_b128 v[182:185], v249 offset:1024
	v_mfma_f32_16x16x32_bf16 v[50:53], v[230:233], v[198:201], v[50:53]
	ds_read_b128 v[186:189], v249 offset:2048
	ds_read_b128 v[190:193], v249 offset:3072
	v_mfma_f32_16x16x32_bf16 v[42:45], v[234:237], v[194:197], v[42:45]
	ds_read_b128 v[194:197], v162 offset:32768
	v_mfma_f32_16x16x32_bf16 v[42:45], v[238:241], v[198:201], v[42:45]
	ds_read_b128 v[198:201], v162 offset:33792
	v_mfma_f32_16x16x32_bf16 v[34:37], v[226:229], v[202:205], v[34:37]
	v_mfma_f32_16x16x32_bf16 v[34:37], v[230:233], v[206:209], v[34:37]
	v_mfma_f32_16x16x32_bf16 v[26:29], v[234:237], v[202:205], v[26:29]
	ds_read_b128 v[202:205], v162 offset:34816
	v_mfma_f32_16x16x32_bf16 v[26:29], v[238:241], v[206:209], v[26:29]
	ds_read_b128 v[206:209], v162 offset:35840
	v_mfma_f32_16x16x32_bf16 v[18:21], v[226:229], v[210:213], v[18:21]
	v_mfma_f32_16x16x32_bf16 v[18:21], v[230:233], v[214:217], v[18:21]
	v_mfma_f32_16x16x32_bf16 v[10:13], v[234:237], v[210:213], v[10:13]
	ds_read_b128 v[210:213], v162 offset:36864
	v_mfma_f32_16x16x32_bf16 v[10:13], v[238:241], v[214:217], v[10:13]
	ds_read_b128 v[214:217], v162 offset:37888
	v_mfma_f32_16x16x32_bf16 v[6:9], v[226:229], v[218:221], v[6:9]
	v_mfma_f32_16x16x32_bf16 v[6:9], v[230:233], v[222:225], v[6:9]
	v_mfma_f32_16x16x32_bf16 v[2:5], v[234:237], v[218:221], v[2:5]
	s_barrier
	v_mfma_f32_16x16x32_bf16 v[2:5], v[238:241], v[222:225], v[2:5]
	s_setprio 0
	s_add_i32 s39, 0, 0x18000
	v_add_u32_e32 v163, s39, v144
	s_add_u32 s24, vcc_lo, 0x40000
	s_addc_u32 s25, vcc_hi, 0
	s_mov_b32 m0, s95
	v_lshl_add_u64 v[226:227], s[24:25], 0, v[136:137]
	ds_read_b128 v[218:221], v162 offset:38912
	ds_read_b128 v[222:225], v162 offset:39936
	global_load_lds_dwordx4 v[226:227], off
	v_lshl_add_u64 v[250:251], s[24:25], 0, v[132:133]
	s_mov_b32 m0, s96
	s_nop 0
	global_load_lds_dwordx4 v[250:251], off
	s_waitcnt lgkmcnt(8)
	s_barrier
	s_waitcnt lgkmcnt(0)
	s_setprio 1
	v_mfma_f32_16x16x32_bf16 v[126:129], v[164:167], v[194:197], v[126:129]
	v_mfma_f32_16x16x32_bf16 v[126:129], v[182:185], v[198:201], v[126:129]
	v_mfma_f32_16x16x32_bf16 v[122:125], v[186:189], v[194:197], v[122:125]
	v_mfma_f32_16x16x32_bf16 v[122:125], v[190:193], v[198:201], v[122:125]
	v_mfma_f32_16x16x32_bf16 v[118:121], v[164:167], v[202:205], v[118:121]
	v_mfma_f32_16x16x32_bf16 v[118:121], v[182:185], v[206:209], v[118:121]
	v_mfma_f32_16x16x32_bf16 v[110:113], v[186:189], v[202:205], v[110:113]
	v_mfma_f32_16x16x32_bf16 v[110:113], v[190:193], v[206:209], v[110:113]
	v_mfma_f32_16x16x32_bf16 v[102:105], v[164:167], v[210:213], v[102:105]
	v_mfma_f32_16x16x32_bf16 v[102:105], v[182:185], v[214:217], v[102:105]
	v_mfma_f32_16x16x32_bf16 v[94:97], v[186:189], v[210:213], v[94:97]
	v_mfma_f32_16x16x32_bf16 v[94:97], v[190:193], v[214:217], v[94:97]
	v_mfma_f32_16x16x32_bf16 v[86:89], v[164:167], v[218:221], v[86:89]
	v_mfma_f32_16x16x32_bf16 v[86:89], v[182:185], v[222:225], v[86:89]
	v_mfma_f32_16x16x32_bf16 v[78:81], v[186:189], v[218:221], v[78:81]
	s_barrier
	v_mfma_f32_16x16x32_bf16 v[78:81], v[190:193], v[222:225], v[78:81]
	s_setprio 0
	s_add_i32 s51, 0, 0x1c000
	s_add_i32 s24, s39, s86
	v_add_u32_e32 v163, s51, v144
	v_lshl_add_u64 v[142:143], v[142:143], 0, s[12:13]
	s_mov_b32 m0, s24
	ds_read_b128 v[226:229], v163
	ds_read_b128 v[230:233], v163 offset:1024
	ds_read_b128 v[234:237], v163 offset:2048
	ds_read_b128 v[238:241], v163 offset:3072
	global_load_lds_dwordx4 v[142:143], off
	v_lshl_add_u64 v[250:251], v[168:169], 0, s[12:13]
	s_add_i32 m0, s24, 0x2000
	s_nop 0
	global_load_lds_dwordx4 v[250:251], off
	s_barrier
	s_waitcnt lgkmcnt(0)
	s_setprio 1
	v_mfma_f32_16x16x32_bf16 v[114:117], v[226:229], v[194:197], v[114:117]
	v_mfma_f32_16x16x32_bf16 v[114:117], v[230:233], v[198:201], v[114:117]
	v_mfma_f32_16x16x32_bf16 v[106:109], v[234:237], v[194:197], v[106:109]
	v_mfma_f32_16x16x32_bf16 v[106:109], v[238:241], v[198:201], v[106:109]
	v_mfma_f32_16x16x32_bf16 v[98:101], v[226:229], v[202:205], v[98:101]
	v_mfma_f32_16x16x32_bf16 v[98:101], v[230:233], v[206:209], v[98:101]
	v_mfma_f32_16x16x32_bf16 v[90:93], v[234:237], v[202:205], v[90:93]
	v_mfma_f32_16x16x32_bf16 v[90:93], v[238:241], v[206:209], v[90:93]
	v_mfma_f32_16x16x32_bf16 v[82:85], v[226:229], v[210:213], v[82:85]
	v_mfma_f32_16x16x32_bf16 v[82:85], v[230:233], v[214:217], v[82:85]
	v_mfma_f32_16x16x32_bf16 v[74:77], v[234:237], v[210:213], v[74:77]
	v_mfma_f32_16x16x32_bf16 v[74:77], v[238:241], v[214:217], v[74:77]
	v_mfma_f32_16x16x32_bf16 v[70:73], v[226:229], v[218:221], v[70:73]
	v_mfma_f32_16x16x32_bf16 v[70:73], v[230:233], v[222:225], v[70:73]
	v_mfma_f32_16x16x32_bf16 v[66:69], v[234:237], v[218:221], v[66:69]
	s_barrier
; #define PG8_STAGE(bufoff, gbase, voff) do { _Pragma("unroll") for (int _i = 0; _i < 2; ++_i) \
;         __builtin_amdgcn_global_load_lds((const unsigned*)((const char*)(gbase) + (voff)[_i]), (LAS unsigned*)(lds + (bufoff) + ldsw + _i * 8192), 16, 0, 0); } while (0)
; #define PG8_LDA(dst, b, h) do { _Pragma("unroll") for (int m = 0; m < 4; ++m) _Pragma("unroll") for (int k = 0; k < 2; ++k) dst[m][k] = *(const LAS bf16x8*)(lds + PG8_SA(b, h) + aoff + m * 2048 + k * 1024); } while (0)
; #define PG8_MMA(ai, bj, At, Bt) do { __builtin_amdgcn_s_setprio(1); _Pragma("unroll") for (int m = 0; m < 4; ++m) _Pragma("unroll") for (int n = 0; n < 2; ++n) _Pragma("unroll") for (int k = 0; k < 2; ++k) \
;         acc[ai][bj][m][n] = __builtin_amdgcn_mfma_f32_16x16x32_bf16(Bt[n][k], At[m][k], acc[ai][bj][m][n], 0, 0, 0); __builtin_amdgcn_s_setprio(0); } while (0)
; #define PG8_WAIT_V(n) asm volatile("s_waitcnt vmcnt(" #n ")" ::: "memory")
; #define PG8_WAIT_L(n) asm volatile("s_waitcnt lgkmcnt(" #n ")" ::: "memory")
; #define PG8_BAR __builtin_amdgcn_s_barrier()
; #define PG8_SCHED __builtin_amdgcn_sched_barrier(0)
; template <class Epi, class Sched>
; __device__ __forceinline__ void gemm_phase(LAS unsigned char* lds, const Gemm g, const Sched& S, const Epi& E) {
;     ...
;             PG8_LDA(At, 1, 1); PG8_STAGE(PG8_SA(1, 0), a3, voffA);
;             PG8_BAR; PG8_WAIT_L(0); PG8_MMA(1, 0, At, B0); PG8_BAR; PG8_SCHED;
;             PG8_STAGE(PG8_SB(1, 1), b3 + hstep, voffB);
;             PG8_WAIT_V(6); PG8_BAR; PG8_MMA(1, 1, At, B1); PG8_BAR;
;         }
;         if (wr == 0) PG8_BAR;
	v_mfma_f32_16x16x32_bf16 v[66:69], v[238:241], v[222:225], v[66:69]
	s_setprio 0
	s_mov_b32 m0, s97
	v_lshl_add_u64 v[142:143], v[242:243], 0, s[12:13]
	ds_read_b128 v[194:197], v162 offset:49152
	ds_read_b128 v[198:201], v162 offset:50176
	ds_read_b128 v[202:205], v162 offset:51200
	ds_read_b128 v[206:209], v162 offset:52224
	ds_read_b128 v[210:213], v162 offset:53248
	ds_read_b128 v[214:217], v162 offset:54272
	ds_read_b128 v[218:221], v162 offset:55296
	ds_read_b128 v[222:225], v162 offset:56320
	global_load_lds_dwordx4 v[142:143], off
	v_lshl_add_u64 v[250:251], v[244:245], 0, s[12:13]
	s_mov_b32 m0, s98
	s_nop 0
	global_load_lds_dwordx4 v[250:251], off
	s_waitcnt vmcnt(8)
	s_barrier
	s_waitcnt lgkmcnt(0)
	s_setprio 1
	v_mfma_f32_16x16x32_bf16 v[62:65], v[164:167], v[194:197], v[62:65]
	v_mfma_f32_16x16x32_bf16 v[62:65], v[182:185], v[198:201], v[62:65]
	v_mfma_f32_16x16x32_bf16 v[58:61], v[186:189], v[194:197], v[58:61]
	v_mfma_f32_16x16x32_bf16 v[58:61], v[190:193], v[198:201], v[58:61]
	v_mfma_f32_16x16x32_bf16 v[54:57], v[164:167], v[202:205], v[54:57]
	v_mfma_f32_16x16x32_bf16 v[54:57], v[182:185], v[206:209], v[54:57]
	v_mfma_f32_16x16x32_bf16 v[46:49], v[186:189], v[202:205], v[46:49]
	v_mfma_f32_16x16x32_bf16 v[46:49], v[190:193], v[206:209], v[46:49]
	v_mfma_f32_16x16x32_bf16 v[38:41], v[164:167], v[210:213], v[38:41]
	v_mfma_f32_16x16x32_bf16 v[38:41], v[182:185], v[214:217], v[38:41]
	v_mfma_f32_16x16x32_bf16 v[30:33], v[186:189], v[210:213], v[30:33]
	v_mfma_f32_16x16x32_bf16 v[30:33], v[190:193], v[214:217], v[30:33]
	v_mfma_f32_16x16x32_bf16 v[22:25], v[164:167], v[218:221], v[22:25]
	v_mfma_f32_16x16x32_bf16 v[22:25], v[182:185], v[222:225], v[22:25]
	v_mfma_f32_16x16x32_bf16 v[14:17], v[186:189], v[218:221], v[14:17]
	s_barrier
	v_mfma_f32_16x16x32_bf16 v[14:17], v[190:193], v[222:225], v[14:17]
	s_setprio 0
	s_add_u32 s24, s36, 0x40080
	s_addc_u32 s25, s37, 0
	s_add_i32 s36, s51, s86
	v_lshl_add_u64 v[142:143], s[24:25], 0, v[134:135]
	s_mov_b32 m0, s36
	s_nop 0
	global_load_lds_dwordx4 v[142:143], off
	v_lshl_add_u64 v[250:251], s[24:25], 0, v[130:131]
	s_add_i32 m0, s36, 0x2000
	s_nop 0
	global_load_lds_dwordx4 v[250:251], off
	s_waitcnt vmcnt(6)
	v_add_u32_e32 v249, 0x10000, v144
	s_barrier
	s_setprio 1
	v_mfma_f32_16x16x32_bf16 v[50:53], v[226:229], v[194:197], v[50:53]
	ds_read_b128 v[164:167], v249
	ds_read_b128 v[182:185], v249 offset:1024
	v_mfma_f32_16x16x32_bf16 v[50:53], v[230:233], v[198:201], v[50:53]
	ds_read_b128 v[186:189], v249 offset:2048
	ds_read_b128 v[190:193], v249 offset:3072
	v_mfma_f32_16x16x32_bf16 v[42:45], v[234:237], v[194:197], v[42:45]
	ds_read_b128 v[194:197], v162
	v_mfma_f32_16x16x32_bf16 v[42:45], v[238:241], v[198:201], v[42:45]
	ds_read_b128 v[198:201], v162 offset:1024
	v_mfma_f32_16x16x32_bf16 v[34:37], v[226:229], v[202:205], v[34:37]
	v_mfma_f32_16x16x32_bf16 v[34:37], v[230:233], v[206:209], v[34:37]
	v_mfma_f32_16x16x32_bf16 v[26:29], v[234:237], v[202:205], v[26:29]
	ds_read_b128 v[202:205], v162 offset:2048
	v_mfma_f32_16x16x32_bf16 v[26:29], v[238:241], v[206:209], v[26:29]
	ds_read_b128 v[206:209], v162 offset:3072
	v_mfma_f32_16x16x32_bf16 v[18:21], v[226:229], v[210:213], v[18:21]
	v_mfma_f32_16x16x32_bf16 v[18:21], v[230:233], v[214:217], v[18:21]
	v_mfma_f32_16x16x32_bf16 v[10:13], v[234:237], v[210:213], v[10:13]
	ds_read_b128 v[210:213], v162 offset:4096
	v_mfma_f32_16x16x32_bf16 v[10:13], v[238:241], v[214:217], v[10:13]
	ds_read_b128 v[214:217], v162 offset:5120
	v_mfma_f32_16x16x32_bf16 v[6:9], v[226:229], v[218:221], v[6:9]
	v_mfma_f32_16x16x32_bf16 v[6:9], v[230:233], v[222:225], v[6:9]
	v_mfma_f32_16x16x32_bf16 v[2:5], v[234:237], v[218:221], v[2:5]
	s_barrier
	v_mfma_f32_16x16x32_bf16 v[2:5], v[238:241], v[222:225], v[2:5]
	s_setprio 0
	s_add_i32 s38, s38, 2
	s_add_u32 s35, s35, 0x100
	s_addc_u32 s50, s50, 0
	s_add_u32 s0, s0, 0x100
	s_addc_u32 s1, s1, 0
	s_cmp_gt_u32 s38, 13
	s_cbranch_scc0 .LBB0_416
	s_waitcnt lgkmcnt(0)
	s_and_b64 vcc, exec, s[44:45]
	s_cbranch_vccz .LBB0_419
	s_barrier

; #define PG8_STAGE(bufoff, gbase, voff) do { _Pragma("unroll") for (int _i = 0; _i < 2; ++_i) \
;         __builtin_amdgcn_global_load_lds((const unsigned*)((const char*)(gbase) + (voff)[_i]), (LAS unsigned*)(lds + (bufoff) + ldsw + _i * 8192), 16, 0, 0); } while (0)
; #define PG8_LDA(dst, b, h) do { _Pragma("unroll") for (int m = 0; m < 4; ++m) _Pragma("unroll") for (int k = 0; k < 2; ++k) dst[m][k] = *(const LAS bf16x8*)(lds + PG8_SA(b, h) + aoff + m * 2048 + k * 1024); } while (0)
; #define PG8_LDB(dst, b, h) do { _Pragma("unroll") for (int n = 0; n < 2; ++n) _Pragma("unroll") for (int k = 0; k < 2; ++k) dst[n][k] = *(const LAS bf16x8*)(lds + PG8_SB(b, h) + boff + n * 2048 + k * 1024); } while (0)
; #define PG8_MMA(ai, bj, At, Bt) do { __builtin_amdgcn_s_setprio(1); _Pragma("unroll") for (int m = 0; m < 4; ++m) _Pragma("unroll") for (int n = 0; n < 2; ++n) _Pragma("unroll") for (int k = 0; k < 2; ++k) \
;         acc[ai][bj][m][n] = __builtin_amdgcn_mfma_f32_16x16x32_bf16(Bt[n][k], At[m][k], acc[ai][bj][m][n], 0, 0, 0); __builtin_amdgcn_s_setprio(0); } while (0)
; #define PG8_WAIT_V(n) asm volatile("s_waitcnt vmcnt(" #n ")" ::: "memory")
; #define PG8_WAIT_L(n) asm volatile("s_waitcnt lgkmcnt(" #n ")" ::: "memory")
; template <class Epi, class Sched>
; __device__ __forceinline__ void gemm_phase(LAS unsigned char* lds, const Gemm g, const Sched& S, const Epi& E) {
;     ...
;         for (int t = 0; t < nt; t += 2) {
;             const bool last = (t == nt - 2);
;             const char* a1 = cA + (size_t)(t + 1) * kstep;
;             const char* a2 = last ? nA : cA + (size_t)(t + 2) * kstep; const char* b2 = last ? nB : cB + (size_t)(t + 2) * kstep;
;             const char* a3 = a2 + kstep; const char* b3 = b2 + kstep;
;             PG8_LDB(B0, 0, 0); PG8_SCHED; PG8_LDA(At, 0, 0); PG8_STAGE(PG8_SA(1, 1), a1 + hstep, voffA);
;             PG8_WAIT_L(8); PG8_BAR; PG8_WAIT_L(0); PG8_MMA(0, 0, At, B0); PG8_BAR; PG8_SCHED;
;             PG8_LDB(B1, 0, 1); PG8_STAGE(PG8_SB(0, 0), b2, voffB);
;             PG8_BAR; PG8_WAIT_L(0); PG8_MMA(0, 1, At, B1); PG8_BAR;
;             PG8_LDA(At, 0, 1); PG8_STAGE(PG8_SA(0, 0), a2, voffA);
;             PG8_BAR; PG8_WAIT_L(0); PG8_MMA(1, 0, At, B0); PG8_BAR; PG8_SCHED;
;             PG8_STAGE(PG8_SB(0, 1), b2 + hstep, voffB);
;             PG8_WAIT_V(6); PG8_BAR; PG8_MMA(1, 1, At, B1); PG8_BAR;
.LBB0_557:
	s_add_u32 s24, s0, 0xfffc0080
	s_addc_u32 s25, s1, -1
	s_add_i32 s39, 0, 0x10000
	v_add_u32_e32 v162, s39, v164
	s_cmp_eq_u32 s38, 12
	s_cselect_b32 vcc_hi, s77, s25
	s_cselect_b32 vcc_lo, s76, s24
	s_cselect_b32 s49, s45, s50
	s_cselect_b32 s48, s47, s35
	v_lshl_add_u64 v[162:163], s[0:1], 0, v[140:141]
	s_add_i32 m0, s95, 0xc000
	ds_read_b128 v[218:221], v166 offset:6144
	ds_read_b128 v[222:225], v166 offset:7168
	global_load_lds_dwordx4 v[162:163], off
	v_lshl_add_u64 v[250:251], s[0:1], 0, v[138:139]
	s_add_i32 m0, s95, 0xe000
	s_nop 0
	global_load_lds_dwordx4 v[250:251], off
	s_waitcnt lgkmcnt(8)
	s_barrier
	s_waitcnt lgkmcnt(0)
	s_setprio 1
	v_mfma_f32_16x16x32_bf16 v[126:129], v[142:145], v[194:197], v[126:129]
	v_mfma_f32_16x16x32_bf16 v[126:129], v[182:185], v[198:201], v[126:129]
	v_mfma_f32_16x16x32_bf16 v[122:125], v[186:189], v[194:197], v[122:125]
	v_mfma_f32_16x16x32_bf16 v[122:125], v[190:193], v[198:201], v[122:125]
	v_mfma_f32_16x16x32_bf16 v[110:113], v[142:145], v[202:205], v[110:113]
	v_mfma_f32_16x16x32_bf16 v[110:113], v[182:185], v[206:209], v[110:113]
	v_mfma_f32_16x16x32_bf16 v[106:109], v[186:189], v[202:205], v[106:109]
	v_mfma_f32_16x16x32_bf16 v[106:109], v[190:193], v[206:209], v[106:109]
	v_mfma_f32_16x16x32_bf16 v[94:97], v[142:145], v[210:213], v[94:97]
	v_mfma_f32_16x16x32_bf16 v[94:97], v[182:185], v[214:217], v[94:97]
	v_mfma_f32_16x16x32_bf16 v[90:93], v[186:189], v[210:213], v[90:93]
	v_mfma_f32_16x16x32_bf16 v[90:93], v[190:193], v[214:217], v[90:93]
	v_mfma_f32_16x16x32_bf16 v[78:81], v[142:145], v[218:221], v[78:81]
	v_mfma_f32_16x16x32_bf16 v[78:81], v[182:185], v[222:225], v[78:81]
	v_mfma_f32_16x16x32_bf16 v[74:77], v[186:189], v[218:221], v[74:77]
	s_barrier
	v_mfma_f32_16x16x32_bf16 v[74:77], v[190:193], v[222:225], v[74:77]
	s_setprio 0
	s_add_i32 s51, 0, 0x14000
	v_add_u32_e32 v162, s51, v164
	s_add_i32 s24, s39, s94
	ds_read_b128 v[226:229], v162
	ds_read_b128 v[230:233], v162 offset:1024
	ds_read_b128 v[234:237], v162 offset:2048
	ds_read_b128 v[238:241], v162 offset:3072
	v_lshl_add_u64 v[162:163], s[48:49], 0, v[134:135]
	s_mov_b32 m0, s24
	v_lshl_add_u64 v[168:169], s[48:49], 0, v[130:131]
	global_load_lds_dwordx4 v[162:163], off
	s_add_i32 m0, s24, 0x2000
	s_nop 0
	global_load_lds_dwordx4 v[168:169], off
	s_barrier
	s_waitcnt lgkmcnt(0)
	s_setprio 1
	v_mfma_f32_16x16x32_bf16 v[118:121], v[226:229], v[194:197], v[118:121]
	v_mfma_f32_16x16x32_bf16 v[118:121], v[230:233], v[198:201], v[118:121]
	v_mfma_f32_16x16x32_bf16 v[114:117], v[234:237], v[194:197], v[114:117]
	v_mfma_f32_16x16x32_bf16 v[114:117], v[238:241], v[198:201], v[114:117]
	v_mfma_f32_16x16x32_bf16 v[102:105], v[226:229], v[202:205], v[102:105]
	v_mfma_f32_16x16x32_bf16 v[102:105], v[230:233], v[206:209], v[102:105]
	v_mfma_f32_16x16x32_bf16 v[98:101], v[234:237], v[202:205], v[98:101]
	v_mfma_f32_16x16x32_bf16 v[98:101], v[238:241], v[206:209], v[98:101]
	v_mfma_f32_16x16x32_bf16 v[86:89], v[226:229], v[210:213], v[86:89]
	v_mfma_f32_16x16x32_bf16 v[86:89], v[230:233], v[214:217], v[86:89]
	v_mfma_f32_16x16x32_bf16 v[82:85], v[234:237], v[210:213], v[82:85]
	v_mfma_f32_16x16x32_bf16 v[82:85], v[238:241], v[214:217], v[82:85]
	v_mfma_f32_16x16x32_bf16 v[70:73], v[226:229], v[218:221], v[70:73]
	v_mfma_f32_16x16x32_bf16 v[70:73], v[230:233], v[222:225], v[70:73]
	v_mfma_f32_16x16x32_bf16 v[66:69], v[234:237], v[218:221], v[66:69]
	s_barrier
	v_mfma_f32_16x16x32_bf16 v[66:69], v[238:241], v[222:225], v[66:69]
	s_setprio 0
	s_mov_b32 m0, s95
	v_lshl_add_u64 v[242:243], vcc, 0, v[136:137]
	ds_read_b128 v[194:197], v166 offset:16384
	ds_read_b128 v[198:201], v166 offset:17408
	ds_read_b128 v[202:205], v166 offset:18432
	ds_read_b128 v[206:209], v166 offset:19456
	ds_read_b128 v[210:213], v166 offset:20480
	ds_read_b128 v[214:217], v166 offset:21504
	ds_read_b128 v[218:221], v166 offset:22528
	ds_read_b128 v[222:225], v166 offset:23552
	global_load_lds_dwordx4 v[242:243], off
	v_lshl_add_u64 v[244:245], vcc, 0, v[132:133]
	s_mov_b32 m0, s96
	s_nop 0
	global_load_lds_dwordx4 v[244:245], off
	s_waitcnt vmcnt(8)
	s_barrier
	s_waitcnt lgkmcnt(0)
	s_setprio 1
	v_mfma_f32_16x16x32_bf16 v[62:65], v[142:145], v[194:197], v[62:65]
	v_mfma_f32_16x16x32_bf16 v[62:65], v[182:185], v[198:201], v[62:65]
	v_mfma_f32_16x16x32_bf16 v[58:61], v[186:189], v[194:197], v[58:61]
	v_mfma_f32_16x16x32_bf16 v[58:61], v[190:193], v[198:201], v[58:61]
	v_mfma_f32_16x16x32_bf16 v[46:49], v[142:145], v[202:205], v[46:49]
	v_mfma_f32_16x16x32_bf16 v[46:49], v[182:185], v[206:209], v[46:49]
	v_mfma_f32_16x16x32_bf16 v[42:45], v[186:189], v[202:205], v[42:45]
	v_mfma_f32_16x16x32_bf16 v[42:45], v[190:193], v[206:209], v[42:45]
	v_mfma_f32_16x16x32_bf16 v[30:33], v[142:145], v[210:213], v[30:33]
	v_mfma_f32_16x16x32_bf16 v[30:33], v[182:185], v[214:217], v[30:33]
	v_mfma_f32_16x16x32_bf16 v[26:29], v[186:189], v[210:213], v[26:29]
	v_mfma_f32_16x16x32_bf16 v[26:29], v[190:193], v[214:217], v[26:29]
	v_mfma_f32_16x16x32_bf16 v[14:17], v[142:145], v[218:221], v[14:17]
	v_mfma_f32_16x16x32_bf16 v[14:17], v[182:185], v[222:225], v[14:17]
	v_mfma_f32_16x16x32_bf16 v[10:13], v[186:189], v[218:221], v[10:13]
	s_barrier
	v_mfma_f32_16x16x32_bf16 v[10:13], v[190:193], v[222:225], v[10:13]
	s_setprio 0
	s_add_u32 s24, s48, 0x40000
	s_addc_u32 s25, s49, 0
	s_add_i32 s39, s51, s94
	v_lshl_add_u64 v[142:143], s[24:25], 0, v[134:135]
	s_mov_b32 m0, s39
	s_nop 0
	global_load_lds_dwordx4 v[142:143], off
	v_lshl_add_u64 v[250:251], s[24:25], 0, v[130:131]
	s_add_i32 m0, s39, 0x2000
	s_nop 0
	global_load_lds_dwordx4 v[250:251], off
	s_waitcnt vmcnt(6)
	v_add_u32_e32 v249, 0x18000, v164
	s_barrier
; #define PG8_STAGE(bufoff, gbase, voff) do { _Pragma("unroll") for (int _i = 0; _i < 2; ++_i) \
;         __builtin_amdgcn_global_load_lds((const unsigned*)((const char*)(gbase) + (voff)[_i]), (LAS unsigned*)(lds + (bufoff) + ldsw + _i * 8192), 16, 0, 0); } while (0)
; #define PG8_LDA(dst, b, h) do { _Pragma("unroll") for (int m = 0; m < 4; ++m) _Pragma("unroll") for (int k = 0; k < 2; ++k) dst[m][k] = *(const LAS bf16x8*)(lds + PG8_SA(b, h) + aoff + m * 2048 + k * 1024); } while (0)
; #define PG8_LDB(dst, b, h) do { _Pragma("unroll") for (int n = 0; n < 2; ++n) _Pragma("unroll") for (int k = 0; k < 2; ++k) dst[n][k] = *(const LAS bf16x8*)(lds + PG8_SB(b, h) + boff + n * 2048 + k * 1024); } while (0)
; #define PG8_MMA(ai, bj, At, Bt) do { __builtin_amdgcn_s_setprio(1); _Pragma("unroll") for (int m = 0; m < 4; ++m) _Pragma("unroll") for (int n = 0; n < 2; ++n) _Pragma("unroll") for (int k = 0; k < 2; ++k) \
;         acc[ai][bj][m][n] = __builtin_amdgcn_mfma_f32_16x16x32_bf16(Bt[n][k], At[m][k], acc[ai][bj][m][n], 0, 0, 0); __builtin_amdgcn_s_setprio(0); } while (0)
; #define PG8_WAIT_V(n) asm volatile("s_waitcnt vmcnt(" #n ")" ::: "memory")
; #define PG8_WAIT_L(n) asm volatile("s_waitcnt lgkmcnt(" #n ")" ::: "memory")
; #define PG8_BAR __builtin_amdgcn_s_barrier()
; #define PG8_SCHED __builtin_amdgcn_sched_barrier(0)
; template <class Epi, class Sched>
; __device__ __forceinline__ void gemm_phase(LAS unsigned char* lds, const Gemm g, const Sched& S, const Epi& E) {
;     ...
;             PG8_WAIT_V(6); PG8_BAR; PG8_MMA(1, 1, At, B1); PG8_BAR;
;             PG8_LDB(B0, 1, 0); PG8_SCHED; PG8_LDA(At, 1, 0); PG8_STAGE(PG8_SA(0, 1), a2 + hstep, voffA);
;             PG8_WAIT_L(8); PG8_BAR; PG8_WAIT_L(0); PG8_MMA(0, 0, At, B0); PG8_BAR; PG8_SCHED;
;             PG8_LDB(B1, 1, 1); PG8_STAGE(PG8_SB(1, 0), b3, voffB);
;             PG8_BAR; PG8_WAIT_L(0); PG8_MMA(0, 1, At, B1); PG8_BAR;
	s_setprio 1
	v_mfma_f32_16x16x32_bf16 v[54:57], v[226:229], v[194:197], v[54:57]
	ds_read_b128 v[142:145], v249
	ds_read_b128 v[182:185], v249 offset:1024
	v_mfma_f32_16x16x32_bf16 v[54:57], v[230:233], v[198:201], v[54:57]
	ds_read_b128 v[186:189], v249 offset:2048
	ds_read_b128 v[190:193], v249 offset:3072
	v_mfma_f32_16x16x32_bf16 v[50:53], v[234:237], v[194:197], v[50:53]
	ds_read_b128 v[194:197], v166 offset:32768
	v_mfma_f32_16x16x32_bf16 v[50:53], v[238:241], v[198:201], v[50:53]
	ds_read_b128 v[198:201], v166 offset:33792
	v_mfma_f32_16x16x32_bf16 v[38:41], v[226:229], v[202:205], v[38:41]
	v_mfma_f32_16x16x32_bf16 v[38:41], v[230:233], v[206:209], v[38:41]
	v_mfma_f32_16x16x32_bf16 v[34:37], v[234:237], v[202:205], v[34:37]
	ds_read_b128 v[202:205], v166 offset:34816
	v_mfma_f32_16x16x32_bf16 v[34:37], v[238:241], v[206:209], v[34:37]
	ds_read_b128 v[206:209], v166 offset:35840
	v_mfma_f32_16x16x32_bf16 v[22:25], v[226:229], v[210:213], v[22:25]
	v_mfma_f32_16x16x32_bf16 v[22:25], v[230:233], v[214:217], v[22:25]
	v_mfma_f32_16x16x32_bf16 v[18:21], v[234:237], v[210:213], v[18:21]
	ds_read_b128 v[210:213], v166 offset:36864
	v_mfma_f32_16x16x32_bf16 v[18:21], v[238:241], v[214:217], v[18:21]
	ds_read_b128 v[214:217], v166 offset:37888
	v_mfma_f32_16x16x32_bf16 v[6:9], v[226:229], v[218:221], v[6:9]
	v_mfma_f32_16x16x32_bf16 v[6:9], v[230:233], v[222:225], v[6:9]
	v_mfma_f32_16x16x32_bf16 v[2:5], v[234:237], v[218:221], v[2:5]
	s_barrier
	v_mfma_f32_16x16x32_bf16 v[2:5], v[238:241], v[222:225], v[2:5]
	s_setprio 0
	s_add_i32 s39, 0, 0x18000
	v_add_u32_e32 v167, s39, v164
	s_add_u32 s24, vcc_lo, 0x40000
	s_addc_u32 s25, vcc_hi, 0
	s_mov_b32 m0, s97
	v_lshl_add_u64 v[226:227], s[24:25], 0, v[136:137]
	ds_read_b128 v[218:221], v166 offset:38912
	ds_read_b128 v[222:225], v166 offset:39936
	global_load_lds_dwordx4 v[226:227], off
	v_lshl_add_u64 v[250:251], s[24:25], 0, v[132:133]
	s_mov_b32 m0, s98
	s_nop 0
	global_load_lds_dwordx4 v[250:251], off
	s_waitcnt lgkmcnt(8)
	s_barrier
	s_waitcnt lgkmcnt(0)
	s_setprio 1
	v_mfma_f32_16x16x32_bf16 v[126:129], v[142:145], v[194:197], v[126:129]
	v_mfma_f32_16x16x32_bf16 v[126:129], v[182:185], v[198:201], v[126:129]
	v_mfma_f32_16x16x32_bf16 v[122:125], v[186:189], v[194:197], v[122:125]
	v_mfma_f32_16x16x32_bf16 v[122:125], v[190:193], v[198:201], v[122:125]
	v_mfma_f32_16x16x32_bf16 v[110:113], v[142:145], v[202:205], v[110:113]
	v_mfma_f32_16x16x32_bf16 v[110:113], v[182:185], v[206:209], v[110:113]
	v_mfma_f32_16x16x32_bf16 v[106:109], v[186:189], v[202:205], v[106:109]
	v_mfma_f32_16x16x32_bf16 v[106:109], v[190:193], v[206:209], v[106:109]
	v_mfma_f32_16x16x32_bf16 v[94:97], v[142:145], v[210:213], v[94:97]
	v_mfma_f32_16x16x32_bf16 v[94:97], v[182:185], v[214:217], v[94:97]
	v_mfma_f32_16x16x32_bf16 v[90:93], v[186:189], v[210:213], v[90:93]
	v_mfma_f32_16x16x32_bf16 v[90:93], v[190:193], v[214:217], v[90:93]
	v_mfma_f32_16x16x32_bf16 v[78:81], v[142:145], v[218:221], v[78:81]
	v_mfma_f32_16x16x32_bf16 v[78:81], v[182:185], v[222:225], v[78:81]
	v_mfma_f32_16x16x32_bf16 v[74:77], v[186:189], v[218:221], v[74:77]
	s_barrier
	v_mfma_f32_16x16x32_bf16 v[74:77], v[190:193], v[222:225], v[74:77]
	s_setprio 0
	s_add_i32 s51, 0, 0x1c000
	s_add_i32 s24, s39, s94
	v_add_u32_e32 v167, s51, v164
	v_lshl_add_u64 v[162:163], v[162:163], 0, s[12:13]
	s_mov_b32 m0, s24
	ds_read_b128 v[226:229], v167
	ds_read_b128 v[230:233], v167 offset:1024
	ds_read_b128 v[234:237], v167 offset:2048
	ds_read_b128 v[238:241], v167 offset:3072
	global_load_lds_dwordx4 v[162:163], off
	v_lshl_add_u64 v[250:251], v[168:169], 0, s[12:13]
	s_add_i32 m0, s24, 0x2000
	s_nop 0
	global_load_lds_dwordx4 v[250:251], off
	s_barrier
	s_waitcnt lgkmcnt(0)
	s_setprio 1
	v_mfma_f32_16x16x32_bf16 v[118:121], v[226:229], v[194:197], v[118:121]
	v_mfma_f32_16x16x32_bf16 v[118:121], v[230:233], v[198:201], v[118:121]
	v_mfma_f32_16x16x32_bf16 v[114:117], v[234:237], v[194:197], v[114:117]
	v_mfma_f32_16x16x32_bf16 v[114:117], v[238:241], v[198:201], v[114:117]
	v_mfma_f32_16x16x32_bf16 v[102:105], v[226:229], v[202:205], v[102:105]
	v_mfma_f32_16x16x32_bf16 v[102:105], v[230:233], v[206:209], v[102:105]
	v_mfma_f32_16x16x32_bf16 v[98:101], v[234:237], v[202:205], v[98:101]
	v_mfma_f32_16x16x32_bf16 v[98:101], v[238:241], v[206:209], v[98:101]
	v_mfma_f32_16x16x32_bf16 v[86:89], v[226:229], v[210:213], v[86:89]
	v_mfma_f32_16x16x32_bf16 v[86:89], v[230:233], v[214:217], v[86:89]
	v_mfma_f32_16x16x32_bf16 v[82:85], v[234:237], v[210:213], v[82:85]
	v_mfma_f32_16x16x32_bf16 v[82:85], v[238:241], v[214:217], v[82:85]
	v_mfma_f32_16x16x32_bf16 v[70:73], v[226:229], v[218:221], v[70:73]
	v_mfma_f32_16x16x32_bf16 v[70:73], v[230:233], v[222:225], v[70:73]
	v_mfma_f32_16x16x32_bf16 v[66:69], v[234:237], v[218:221], v[66:69]
	s_barrier
; #define PG8_STAGE(bufoff, gbase, voff) do { _Pragma("unroll") for (int _i = 0; _i < 2; ++_i) \
;         __builtin_amdgcn_global_load_lds((const unsigned*)((const char*)(gbase) + (voff)[_i]), (LAS unsigned*)(lds + (bufoff) + ldsw + _i * 8192), 16, 0, 0); } while (0)
; #define PG8_LDA(dst, b, h) do { _Pragma("unroll") for (int m = 0; m < 4; ++m) _Pragma("unroll") for (int k = 0; k < 2; ++k) dst[m][k] = *(const LAS bf16x8*)(lds + PG8_SA(b, h) + aoff + m * 2048 + k * 1024); } while (0)
; #define PG8_MMA(ai, bj, At, Bt) do { __builtin_amdgcn_s_setprio(1); _Pragma("unroll") for (int m = 0; m < 4; ++m) _Pragma("unroll") for (int n = 0; n < 2; ++n) _Pragma("unroll") for (int k = 0; k < 2; ++k) \
;         acc[ai][bj][m][n] = __builtin_amdgcn_mfma_f32_16x16x32_bf16(Bt[n][k], At[m][k], acc[ai][bj][m][n], 0, 0, 0); __builtin_amdgcn_s_setprio(0); } while (0)
; #define PG8_WAIT_V(n) asm volatile("s_waitcnt vmcnt(" #n ")" ::: "memory")
; #define PG8_WAIT_L(n) asm volatile("s_waitcnt lgkmcnt(" #n ")" ::: "memory")
; #define PG8_BAR __builtin_amdgcn_s_barrier()
; #define PG8_SCHED __builtin_amdgcn_sched_barrier(0)
; template <class Epi, class Sched>
; __device__ __forceinline__ void gemm_phase(LAS unsigned char* lds, const Gemm g, const Sched& S, const Epi& E) {
;     ...
;             PG8_LDA(At, 1, 1); PG8_STAGE(PG8_SA(1, 0), a3, voffA);
;             PG8_BAR; PG8_WAIT_L(0); PG8_MMA(1, 0, At, B0); PG8_BAR; PG8_SCHED;
;             PG8_STAGE(PG8_SB(1, 1), b3 + hstep, voffB);
;             PG8_WAIT_V(6); PG8_BAR; PG8_MMA(1, 1, At, B1); PG8_BAR;
;         }
;         if (wr == 0) PG8_BAR;
	v_mfma_f32_16x16x32_bf16 v[66:69], v[238:241], v[222:225], v[66:69]
	s_setprio 0
	s_mov_b32 m0, s99
	v_lshl_add_u64 v[162:163], v[242:243], 0, s[12:13]
	ds_read_b128 v[194:197], v166 offset:49152
	ds_read_b128 v[198:201], v166 offset:50176
	ds_read_b128 v[202:205], v166 offset:51200
	ds_read_b128 v[206:209], v166 offset:52224
	ds_read_b128 v[210:213], v166 offset:53248
	ds_read_b128 v[214:217], v166 offset:54272
	ds_read_b128 v[218:221], v166 offset:55296
	ds_read_b128 v[222:225], v166 offset:56320
	global_load_lds_dwordx4 v[162:163], off
	v_lshl_add_u64 v[250:251], v[244:245], 0, s[12:13]
	s_mov_b32 m0, s82
	s_nop 0
	global_load_lds_dwordx4 v[250:251], off
	s_waitcnt vmcnt(8)
	s_barrier
	s_waitcnt lgkmcnt(0)
	s_setprio 1
	v_mfma_f32_16x16x32_bf16 v[62:65], v[142:145], v[194:197], v[62:65]
	v_mfma_f32_16x16x32_bf16 v[62:65], v[182:185], v[198:201], v[62:65]
	v_mfma_f32_16x16x32_bf16 v[58:61], v[186:189], v[194:197], v[58:61]
	v_mfma_f32_16x16x32_bf16 v[58:61], v[190:193], v[198:201], v[58:61]
	v_mfma_f32_16x16x32_bf16 v[46:49], v[142:145], v[202:205], v[46:49]
	v_mfma_f32_16x16x32_bf16 v[46:49], v[182:185], v[206:209], v[46:49]
	v_mfma_f32_16x16x32_bf16 v[42:45], v[186:189], v[202:205], v[42:45]
	v_mfma_f32_16x16x32_bf16 v[42:45], v[190:193], v[206:209], v[42:45]
	v_mfma_f32_16x16x32_bf16 v[30:33], v[142:145], v[210:213], v[30:33]
	v_mfma_f32_16x16x32_bf16 v[30:33], v[182:185], v[214:217], v[30:33]
	v_mfma_f32_16x16x32_bf16 v[26:29], v[186:189], v[210:213], v[26:29]
	v_mfma_f32_16x16x32_bf16 v[26:29], v[190:193], v[214:217], v[26:29]
	v_mfma_f32_16x16x32_bf16 v[14:17], v[142:145], v[218:221], v[14:17]
	v_mfma_f32_16x16x32_bf16 v[14:17], v[182:185], v[222:225], v[14:17]
	v_mfma_f32_16x16x32_bf16 v[10:13], v[186:189], v[218:221], v[10:13]
	s_barrier
	v_mfma_f32_16x16x32_bf16 v[10:13], v[190:193], v[222:225], v[10:13]
	s_setprio 0
	s_add_u32 s24, s48, 0x40080
	s_addc_u32 s25, s49, 0
	s_add_i32 s39, s51, s94
	v_lshl_add_u64 v[142:143], s[24:25], 0, v[134:135]
	s_mov_b32 m0, s39
	s_nop 0
	global_load_lds_dwordx4 v[142:143], off
	v_lshl_add_u64 v[250:251], s[24:25], 0, v[130:131]
	s_add_i32 m0, s39, 0x2000
	s_nop 0
	global_load_lds_dwordx4 v[250:251], off
	s_waitcnt vmcnt(6)
	v_add_u32_e32 v249, 0x10000, v164
	s_barrier
	s_setprio 1
	v_mfma_f32_16x16x32_bf16 v[54:57], v[226:229], v[194:197], v[54:57]
	ds_read_b128 v[142:145], v249
	ds_read_b128 v[182:185], v249 offset:1024
	v_mfma_f32_16x16x32_bf16 v[54:57], v[230:233], v[198:201], v[54:57]
	ds_read_b128 v[186:189], v249 offset:2048
	ds_read_b128 v[190:193], v249 offset:3072
	v_mfma_f32_16x16x32_bf16 v[50:53], v[234:237], v[194:197], v[50:53]
	ds_read_b128 v[194:197], v166
	v_mfma_f32_16x16x32_bf16 v[50:53], v[238:241], v[198:201], v[50:53]
	ds_read_b128 v[198:201], v166 offset:1024
	v_mfma_f32_16x16x32_bf16 v[38:41], v[226:229], v[202:205], v[38:41]
	v_mfma_f32_16x16x32_bf16 v[38:41], v[230:233], v[206:209], v[38:41]
	v_mfma_f32_16x16x32_bf16 v[34:37], v[234:237], v[202:205], v[34:37]
	ds_read_b128 v[202:205], v166 offset:2048
	v_mfma_f32_16x16x32_bf16 v[34:37], v[238:241], v[206:209], v[34:37]
	ds_read_b128 v[206:209], v166 offset:3072
	v_mfma_f32_16x16x32_bf16 v[22:25], v[226:229], v[210:213], v[22:25]
	v_mfma_f32_16x16x32_bf16 v[22:25], v[230:233], v[214:217], v[22:25]
	v_mfma_f32_16x16x32_bf16 v[18:21], v[234:237], v[210:213], v[18:21]
	ds_read_b128 v[210:213], v166 offset:4096
	v_mfma_f32_16x16x32_bf16 v[18:21], v[238:241], v[214:217], v[18:21]
	ds_read_b128 v[214:217], v166 offset:5120
	v_mfma_f32_16x16x32_bf16 v[6:9], v[226:229], v[218:221], v[6:9]
	v_mfma_f32_16x16x32_bf16 v[6:9], v[230:233], v[222:225], v[6:9]
	v_mfma_f32_16x16x32_bf16 v[2:5], v[234:237], v[218:221], v[2:5]
	s_barrier
	v_mfma_f32_16x16x32_bf16 v[2:5], v[238:241], v[222:225], v[2:5]
	s_setprio 0
	s_add_i32 s38, s38, 2
	s_add_u32 s35, s35, 0x100
	s_addc_u32 s50, s50, 0
	s_add_u32 s0, s0, 0x100
	s_addc_u32 s1, s1, 0
	s_cmp_gt_u32 s38, 13
	s_cbranch_scc0 .LBB0_557
	s_waitcnt lgkmcnt(0)
	s_and_b64 vcc, exec, s[42:43]
	s_cbranch_vccz .LBB0_560
	s_barrier

; #define PG8_STAGE(bufoff, gbase, voff) do { _Pragma("unroll") for (int _i = 0; _i < 2; ++_i) \
;         __builtin_amdgcn_global_load_lds((const unsigned*)((const char*)(gbase) + (voff)[_i]), (LAS unsigned*)(lds + (bufoff) + ldsw + _i * 8192), 16, 0, 0); } while (0)
; #define PG8_LDA(dst, b, h) do { _Pragma("unroll") for (int m = 0; m < 4; ++m) _Pragma("unroll") for (int k = 0; k < 2; ++k) dst[m][k] = *(const LAS bf16x8*)(lds + PG8_SA(b, h) + aoff + m * 2048 + k * 1024); } while (0)
; #define PG8_LDB(dst, b, h) do { _Pragma("unroll") for (int n = 0; n < 2; ++n) _Pragma("unroll") for (int k = 0; k < 2; ++k) dst[n][k] = *(const LAS bf16x8*)(lds + PG8_SB(b, h) + boff + n * 2048 + k * 1024); } while (0)
; #define PG8_MMA(ai, bj, At, Bt) do { __builtin_amdgcn_s_setprio(1); _Pragma("unroll") for (int m = 0; m < 4; ++m) _Pragma("unroll") for (int n = 0; n < 2; ++n) _Pragma("unroll") for (int k = 0; k < 2; ++k) \
;         acc[ai][bj][m][n] = __builtin_amdgcn_mfma_f32_16x16x32_bf16(Bt[n][k], At[m][k], acc[ai][bj][m][n], 0, 0, 0); __builtin_amdgcn_s_setprio(0); } while (0)
; #define PG8_WAIT_V(n) asm volatile("s_waitcnt vmcnt(" #n ")" ::: "memory")
; #define PG8_WAIT_L(n) asm volatile("s_waitcnt lgkmcnt(" #n ")" ::: "memory")
; template <class Epi, class Sched>
; __device__ __forceinline__ void gemm_phase(LAS unsigned char* lds, const Gemm g, const Sched& S, const Epi& E) {
;     ...
;         for (int t = 0; t < nt; t += 2) {
;             const bool last = (t == nt - 2);
;             const char* a1 = cA + (size_t)(t + 1) * kstep;
;             const char* a2 = last ? nA : cA + (size_t)(t + 2) * kstep; const char* b2 = last ? nB : cB + (size_t)(t + 2) * kstep;
;             const char* a3 = a2 + kstep; const char* b3 = b2 + kstep;
;             PG8_LDB(B0, 0, 0); PG8_SCHED; PG8_LDA(At, 0, 0); PG8_STAGE(PG8_SA(1, 1), a1 + hstep, voffA);
;             PG8_WAIT_L(8); PG8_BAR; PG8_WAIT_L(0); PG8_MMA(0, 0, At, B0); PG8_BAR; PG8_SCHED;
;             PG8_LDB(B1, 0, 1); PG8_STAGE(PG8_SB(0, 0), b2, voffB);
;             PG8_BAR; PG8_WAIT_L(0); PG8_MMA(0, 1, At, B1); PG8_BAR;
;             PG8_LDA(At, 0, 1); PG8_STAGE(PG8_SA(0, 0), a2, voffA);
;             PG8_BAR; PG8_WAIT_L(0); PG8_MMA(1, 0, At, B0); PG8_BAR; PG8_SCHED;
;             PG8_STAGE(PG8_SB(0, 1), b2 + hstep, voffB);
;             PG8_WAIT_V(6); PG8_BAR; PG8_MMA(1, 1, At, B1); PG8_BAR;
.LBB0_627:
	s_add_u32 s24, s0, 0xfff00080
	s_addc_u32 s25, s1, -1
	s_add_i32 s51, 0, 0x10000
	v_add_u32_e32 v142, s51, v144
	s_cmp_eq_u32 s98, 60
	s_cselect_b32 s77, s47, s25
	s_cselect_b32 s76, s46, s24
	s_cselect_b32 s49, s43, s50
	s_cselect_b32 s48, s45, s35
	v_lshl_add_u64 v[142:143], s[0:1], 0, v[140:141]
	s_add_i32 m0, s86, 0xc000
	ds_read_b128 v[218:221], v162 offset:6144
	ds_read_b128 v[222:225], v162 offset:7168
	global_load_lds_dwordx4 v[142:143], off
	v_lshl_add_u64 v[250:251], s[0:1], 0, v[138:139]
	s_add_i32 m0, s86, 0xe000
	s_nop 0
	global_load_lds_dwordx4 v[250:251], off
	s_waitcnt lgkmcnt(8)
	s_barrier
	s_waitcnt lgkmcnt(0)
	s_setprio 1
	v_mfma_f32_16x16x32_bf16 v[126:129], v[164:167], v[194:197], v[126:129]
	v_mfma_f32_16x16x32_bf16 v[126:129], v[182:185], v[198:201], v[126:129]
	v_mfma_f32_16x16x32_bf16 v[122:125], v[186:189], v[194:197], v[122:125]
	v_mfma_f32_16x16x32_bf16 v[122:125], v[190:193], v[198:201], v[122:125]
	v_mfma_f32_16x16x32_bf16 v[118:121], v[164:167], v[202:205], v[118:121]
	v_mfma_f32_16x16x32_bf16 v[118:121], v[182:185], v[206:209], v[118:121]
	v_mfma_f32_16x16x32_bf16 v[110:113], v[186:189], v[202:205], v[110:113]
	v_mfma_f32_16x16x32_bf16 v[110:113], v[190:193], v[206:209], v[110:113]
	v_mfma_f32_16x16x32_bf16 v[102:105], v[164:167], v[210:213], v[102:105]
	v_mfma_f32_16x16x32_bf16 v[102:105], v[182:185], v[214:217], v[102:105]
	v_mfma_f32_16x16x32_bf16 v[94:97], v[186:189], v[210:213], v[94:97]
	v_mfma_f32_16x16x32_bf16 v[94:97], v[190:193], v[214:217], v[94:97]
	v_mfma_f32_16x16x32_bf16 v[86:89], v[164:167], v[218:221], v[86:89]
	v_mfma_f32_16x16x32_bf16 v[86:89], v[182:185], v[222:225], v[86:89]
	v_mfma_f32_16x16x32_bf16 v[78:81], v[186:189], v[218:221], v[78:81]
	s_barrier
	v_mfma_f32_16x16x32_bf16 v[78:81], v[190:193], v[222:225], v[78:81]
	s_setprio 0
	s_add_i32 s99, 0, 0x14000
	v_add_u32_e32 v142, s99, v144
	s_add_i32 s24, s51, s83
	ds_read_b128 v[226:229], v142
	ds_read_b128 v[230:233], v142 offset:1024
	ds_read_b128 v[234:237], v142 offset:2048
	ds_read_b128 v[238:241], v142 offset:3072
	v_lshl_add_u64 v[142:143], s[48:49], 0, v[134:135]
	s_mov_b32 m0, s24
	v_lshl_add_u64 v[168:169], s[48:49], 0, v[130:131]
	global_load_lds_dwordx4 v[142:143], off
	s_add_i32 m0, s24, 0x2000
	s_nop 0
	global_load_lds_dwordx4 v[168:169], off
	s_barrier
	s_waitcnt lgkmcnt(0)
	s_setprio 1
	v_mfma_f32_16x16x32_bf16 v[114:117], v[226:229], v[194:197], v[114:117]
	v_mfma_f32_16x16x32_bf16 v[114:117], v[230:233], v[198:201], v[114:117]
	v_mfma_f32_16x16x32_bf16 v[106:109], v[234:237], v[194:197], v[106:109]
	v_mfma_f32_16x16x32_bf16 v[106:109], v[238:241], v[198:201], v[106:109]
	v_mfma_f32_16x16x32_bf16 v[98:101], v[226:229], v[202:205], v[98:101]
	v_mfma_f32_16x16x32_bf16 v[98:101], v[230:233], v[206:209], v[98:101]
	v_mfma_f32_16x16x32_bf16 v[90:93], v[234:237], v[202:205], v[90:93]
	v_mfma_f32_16x16x32_bf16 v[90:93], v[238:241], v[206:209], v[90:93]
	v_mfma_f32_16x16x32_bf16 v[82:85], v[226:229], v[210:213], v[82:85]
	v_mfma_f32_16x16x32_bf16 v[82:85], v[230:233], v[214:217], v[82:85]
	v_mfma_f32_16x16x32_bf16 v[74:77], v[234:237], v[210:213], v[74:77]
	v_mfma_f32_16x16x32_bf16 v[74:77], v[238:241], v[214:217], v[74:77]
	v_mfma_f32_16x16x32_bf16 v[70:73], v[226:229], v[218:221], v[70:73]
	v_mfma_f32_16x16x32_bf16 v[70:73], v[230:233], v[222:225], v[70:73]
	v_mfma_f32_16x16x32_bf16 v[66:69], v[234:237], v[218:221], v[66:69]
	s_barrier
	v_mfma_f32_16x16x32_bf16 v[66:69], v[238:241], v[222:225], v[66:69]
	s_setprio 0
	s_mov_b32 m0, s86
	v_lshl_add_u64 v[242:243], s[76:77], 0, v[136:137]
	ds_read_b128 v[194:197], v162 offset:16384
	ds_read_b128 v[198:201], v162 offset:17408
	ds_read_b128 v[202:205], v162 offset:18432
	ds_read_b128 v[206:209], v162 offset:19456
	ds_read_b128 v[210:213], v162 offset:20480
	ds_read_b128 v[214:217], v162 offset:21504
	ds_read_b128 v[218:221], v162 offset:22528
	ds_read_b128 v[222:225], v162 offset:23552
	global_load_lds_dwordx4 v[242:243], off
	v_lshl_add_u64 v[244:245], s[76:77], 0, v[132:133]
	s_mov_b32 m0, s92
	s_nop 0
	global_load_lds_dwordx4 v[244:245], off
	s_waitcnt vmcnt(8)
	s_barrier
	s_waitcnt lgkmcnt(0)
	s_setprio 1
	v_mfma_f32_16x16x32_bf16 v[62:65], v[164:167], v[194:197], v[62:65]
	v_mfma_f32_16x16x32_bf16 v[62:65], v[182:185], v[198:201], v[62:65]
	v_mfma_f32_16x16x32_bf16 v[58:61], v[186:189], v[194:197], v[58:61]
	v_mfma_f32_16x16x32_bf16 v[58:61], v[190:193], v[198:201], v[58:61]
	v_mfma_f32_16x16x32_bf16 v[54:57], v[164:167], v[202:205], v[54:57]
	v_mfma_f32_16x16x32_bf16 v[54:57], v[182:185], v[206:209], v[54:57]
	v_mfma_f32_16x16x32_bf16 v[46:49], v[186:189], v[202:205], v[46:49]
	v_mfma_f32_16x16x32_bf16 v[46:49], v[190:193], v[206:209], v[46:49]
	v_mfma_f32_16x16x32_bf16 v[38:41], v[164:167], v[210:213], v[38:41]
	v_mfma_f32_16x16x32_bf16 v[38:41], v[182:185], v[214:217], v[38:41]
	v_mfma_f32_16x16x32_bf16 v[30:33], v[186:189], v[210:213], v[30:33]
	v_mfma_f32_16x16x32_bf16 v[30:33], v[190:193], v[214:217], v[30:33]
	v_mfma_f32_16x16x32_bf16 v[22:25], v[164:167], v[218:221], v[22:25]
	v_mfma_f32_16x16x32_bf16 v[22:25], v[182:185], v[222:225], v[22:25]
	v_mfma_f32_16x16x32_bf16 v[14:17], v[186:189], v[218:221], v[14:17]
	s_barrier
	v_mfma_f32_16x16x32_bf16 v[14:17], v[190:193], v[222:225], v[14:17]
	s_setprio 0
	s_add_u32 s24, s48, 0x100000
	s_addc_u32 s25, s49, 0
	s_add_i32 s51, s99, s83
	v_lshl_add_u64 v[164:165], s[24:25], 0, v[134:135]
	s_mov_b32 m0, s51
	s_nop 0
	global_load_lds_dwordx4 v[164:165], off
	v_lshl_add_u64 v[250:251], s[24:25], 0, v[130:131]
	s_add_i32 m0, s51, 0x2000
	s_nop 0
	global_load_lds_dwordx4 v[250:251], off
	s_waitcnt vmcnt(6)
	v_add_u32_e32 v249, 0x18000, v144
	s_barrier
; #define PG8_STAGE(bufoff, gbase, voff) do { _Pragma("unroll") for (int _i = 0; _i < 2; ++_i) \
;         __builtin_amdgcn_global_load_lds((const unsigned*)((const char*)(gbase) + (voff)[_i]), (LAS unsigned*)(lds + (bufoff) + ldsw + _i * 8192), 16, 0, 0); } while (0)
; #define PG8_LDA(dst, b, h) do { _Pragma("unroll") for (int m = 0; m < 4; ++m) _Pragma("unroll") for (int k = 0; k < 2; ++k) dst[m][k] = *(const LAS bf16x8*)(lds + PG8_SA(b, h) + aoff + m * 2048 + k * 1024); } while (0)
; #define PG8_LDB(dst, b, h) do { _Pragma("unroll") for (int n = 0; n < 2; ++n) _Pragma("unroll") for (int k = 0; k < 2; ++k) dst[n][k] = *(const LAS bf16x8*)(lds + PG8_SB(b, h) + boff + n * 2048 + k * 1024); } while (0)
; #define PG8_MMA(ai, bj, At, Bt) do { __builtin_amdgcn_s_setprio(1); _Pragma("unroll") for (int m = 0; m < 4; ++m) _Pragma("unroll") for (int n = 0; n < 2; ++n) _Pragma("unroll") for (int k = 0; k < 2; ++k) \
;         acc[ai][bj][m][n] = __builtin_amdgcn_mfma_f32_16x16x32_bf16(Bt[n][k], At[m][k], acc[ai][bj][m][n], 0, 0, 0); __builtin_amdgcn_s_setprio(0); } while (0)
; #define PG8_WAIT_V(n) asm volatile("s_waitcnt vmcnt(" #n ")" ::: "memory")
; #define PG8_WAIT_L(n) asm volatile("s_waitcnt lgkmcnt(" #n ")" ::: "memory")
; #define PG8_BAR __builtin_amdgcn_s_barrier()
; #define PG8_SCHED __builtin_amdgcn_sched_barrier(0)
; template <class Epi, class Sched>
; __device__ __forceinline__ void gemm_phase(LAS unsigned char* lds, const Gemm g, const Sched& S, const Epi& E) {
;     ...
;             PG8_WAIT_V(6); PG8_BAR; PG8_MMA(1, 1, At, B1); PG8_BAR;
;             PG8_LDB(B0, 1, 0); PG8_SCHED; PG8_LDA(At, 1, 0); PG8_STAGE(PG8_SA(0, 1), a2 + hstep, voffA);
;             PG8_WAIT_L(8); PG8_BAR; PG8_WAIT_L(0); PG8_MMA(0, 0, At, B0); PG8_BAR; PG8_SCHED;
;             PG8_LDB(B1, 1, 1); PG8_STAGE(PG8_SB(1, 0), b3, voffB);
;             PG8_BAR; PG8_WAIT_L(0); PG8_MMA(0, 1, At, B1); PG8_BAR;
	s_setprio 1
	v_mfma_f32_16x16x32_bf16 v[50:53], v[226:229], v[194:197], v[50:53]
	ds_read_b128 v[164:167], v249
	ds_read_b128 v[182:185], v249 offset:1024
	v_mfma_f32_16x16x32_bf16 v[50:53], v[230:233], v[198:201], v[50:53]
	ds_read_b128 v[186:189], v249 offset:2048
	ds_read_b128 v[190:193], v249 offset:3072
	v_mfma_f32_16x16x32_bf16 v[42:45], v[234:237], v[194:197], v[42:45]
	ds_read_b128 v[194:197], v162 offset:32768
	v_mfma_f32_16x16x32_bf16 v[42:45], v[238:241], v[198:201], v[42:45]
	ds_read_b128 v[198:201], v162 offset:33792
	v_mfma_f32_16x16x32_bf16 v[34:37], v[226:229], v[202:205], v[34:37]
	v_mfma_f32_16x16x32_bf16 v[34:37], v[230:233], v[206:209], v[34:37]
	v_mfma_f32_16x16x32_bf16 v[26:29], v[234:237], v[202:205], v[26:29]
	ds_read_b128 v[202:205], v162 offset:34816
	v_mfma_f32_16x16x32_bf16 v[26:29], v[238:241], v[206:209], v[26:29]
	ds_read_b128 v[206:209], v162 offset:35840
	v_mfma_f32_16x16x32_bf16 v[18:21], v[226:229], v[210:213], v[18:21]
	v_mfma_f32_16x16x32_bf16 v[18:21], v[230:233], v[214:217], v[18:21]
	v_mfma_f32_16x16x32_bf16 v[10:13], v[234:237], v[210:213], v[10:13]
	ds_read_b128 v[210:213], v162 offset:36864
	v_mfma_f32_16x16x32_bf16 v[10:13], v[238:241], v[214:217], v[10:13]
	ds_read_b128 v[214:217], v162 offset:37888
	v_mfma_f32_16x16x32_bf16 v[6:9], v[226:229], v[218:221], v[6:9]
	v_mfma_f32_16x16x32_bf16 v[6:9], v[230:233], v[222:225], v[6:9]
	v_mfma_f32_16x16x32_bf16 v[2:5], v[234:237], v[218:221], v[2:5]
	s_barrier
	v_mfma_f32_16x16x32_bf16 v[2:5], v[238:241], v[222:225], v[2:5]
	s_setprio 0
	s_add_i32 s51, 0, 0x18000
	v_add_u32_e32 v163, s51, v144
	s_add_u32 s24, s76, 0x100000
	s_addc_u32 s25, s77, 0
	s_mov_b32 m0, s93
	v_lshl_add_u64 v[226:227], s[24:25], 0, v[136:137]
	ds_read_b128 v[218:221], v162 offset:38912
	ds_read_b128 v[222:225], v162 offset:39936
	global_load_lds_dwordx4 v[226:227], off
	v_lshl_add_u64 v[250:251], s[24:25], 0, v[132:133]
	s_mov_b32 m0, s94
	s_nop 0
	global_load_lds_dwordx4 v[250:251], off
	s_waitcnt lgkmcnt(8)
	s_barrier
	s_waitcnt lgkmcnt(0)
	s_setprio 1
	v_mfma_f32_16x16x32_bf16 v[126:129], v[164:167], v[194:197], v[126:129]
	v_mfma_f32_16x16x32_bf16 v[126:129], v[182:185], v[198:201], v[126:129]
	v_mfma_f32_16x16x32_bf16 v[122:125], v[186:189], v[194:197], v[122:125]
	v_mfma_f32_16x16x32_bf16 v[122:125], v[190:193], v[198:201], v[122:125]
	v_mfma_f32_16x16x32_bf16 v[118:121], v[164:167], v[202:205], v[118:121]
	v_mfma_f32_16x16x32_bf16 v[118:121], v[182:185], v[206:209], v[118:121]
	v_mfma_f32_16x16x32_bf16 v[110:113], v[186:189], v[202:205], v[110:113]
	v_mfma_f32_16x16x32_bf16 v[110:113], v[190:193], v[206:209], v[110:113]
	v_mfma_f32_16x16x32_bf16 v[102:105], v[164:167], v[210:213], v[102:105]
	v_mfma_f32_16x16x32_bf16 v[102:105], v[182:185], v[214:217], v[102:105]
	v_mfma_f32_16x16x32_bf16 v[94:97], v[186:189], v[210:213], v[94:97]
	v_mfma_f32_16x16x32_bf16 v[94:97], v[190:193], v[214:217], v[94:97]
	v_mfma_f32_16x16x32_bf16 v[86:89], v[164:167], v[218:221], v[86:89]
	v_mfma_f32_16x16x32_bf16 v[86:89], v[182:185], v[222:225], v[86:89]
	v_mfma_f32_16x16x32_bf16 v[78:81], v[186:189], v[218:221], v[78:81]
	s_barrier
	v_mfma_f32_16x16x32_bf16 v[78:81], v[190:193], v[222:225], v[78:81]
	s_setprio 0
	s_add_i32 s76, 0, 0x1c000
	s_add_i32 s24, s51, s83
	v_add_u32_e32 v163, s76, v144
	v_lshl_add_u64 v[142:143], v[142:143], 0, s[12:13]
	s_mov_b32 m0, s24
	ds_read_b128 v[226:229], v163
	ds_read_b128 v[230:233], v163 offset:1024
	ds_read_b128 v[234:237], v163 offset:2048
	ds_read_b128 v[238:241], v163 offset:3072
	global_load_lds_dwordx4 v[142:143], off
	v_lshl_add_u64 v[250:251], v[168:169], 0, s[12:13]
	s_add_i32 m0, s24, 0x2000
	s_nop 0
	global_load_lds_dwordx4 v[250:251], off
	s_barrier
	s_waitcnt lgkmcnt(0)
	s_setprio 1
	v_mfma_f32_16x16x32_bf16 v[114:117], v[226:229], v[194:197], v[114:117]
	v_mfma_f32_16x16x32_bf16 v[114:117], v[230:233], v[198:201], v[114:117]
	v_mfma_f32_16x16x32_bf16 v[106:109], v[234:237], v[194:197], v[106:109]
	v_mfma_f32_16x16x32_bf16 v[106:109], v[238:241], v[198:201], v[106:109]
	v_mfma_f32_16x16x32_bf16 v[98:101], v[226:229], v[202:205], v[98:101]
	v_mfma_f32_16x16x32_bf16 v[98:101], v[230:233], v[206:209], v[98:101]
	v_mfma_f32_16x16x32_bf16 v[90:93], v[234:237], v[202:205], v[90:93]
	v_mfma_f32_16x16x32_bf16 v[90:93], v[238:241], v[206:209], v[90:93]
	v_mfma_f32_16x16x32_bf16 v[82:85], v[226:229], v[210:213], v[82:85]
	v_mfma_f32_16x16x32_bf16 v[82:85], v[230:233], v[214:217], v[82:85]
	v_mfma_f32_16x16x32_bf16 v[74:77], v[234:237], v[210:213], v[74:77]
	v_mfma_f32_16x16x32_bf16 v[74:77], v[238:241], v[214:217], v[74:77]
	v_mfma_f32_16x16x32_bf16 v[70:73], v[226:229], v[218:221], v[70:73]
	v_mfma_f32_16x16x32_bf16 v[70:73], v[230:233], v[222:225], v[70:73]
	v_mfma_f32_16x16x32_bf16 v[66:69], v[234:237], v[218:221], v[66:69]
	s_barrier
; #define PG8_STAGE(bufoff, gbase, voff) do { _Pragma("unroll") for (int _i = 0; _i < 2; ++_i) \
;         __builtin_amdgcn_global_load_lds((const unsigned*)((const char*)(gbase) + (voff)[_i]), (LAS unsigned*)(lds + (bufoff) + ldsw + _i * 8192), 16, 0, 0); } while (0)
; #define PG8_LDA(dst, b, h) do { _Pragma("unroll") for (int m = 0; m < 4; ++m) _Pragma("unroll") for (int k = 0; k < 2; ++k) dst[m][k] = *(const LAS bf16x8*)(lds + PG8_SA(b, h) + aoff + m * 2048 + k * 1024); } while (0)
; #define PG8_MMA(ai, bj, At, Bt) do { __builtin_amdgcn_s_setprio(1); _Pragma("unroll") for (int m = 0; m < 4; ++m) _Pragma("unroll") for (int n = 0; n < 2; ++n) _Pragma("unroll") for (int k = 0; k < 2; ++k) \
;         acc[ai][bj][m][n] = __builtin_amdgcn_mfma_f32_16x16x32_bf16(Bt[n][k], At[m][k], acc[ai][bj][m][n], 0, 0, 0); __builtin_amdgcn_s_setprio(0); } while (0)
; #define PG8_WAIT_V(n) asm volatile("s_waitcnt vmcnt(" #n ")" ::: "memory")
; #define PG8_WAIT_L(n) asm volatile("s_waitcnt lgkmcnt(" #n ")" ::: "memory")
; #define PG8_BAR __builtin_amdgcn_s_barrier()
; #define PG8_SCHED __builtin_amdgcn_sched_barrier(0)
; template <class Epi, class Sched>
; __device__ __forceinline__ void gemm_phase(LAS unsigned char* lds, const Gemm g, const Sched& S, const Epi& E) {
;     ...
;             PG8_LDA(At, 1, 1); PG8_STAGE(PG8_SA(1, 0), a3, voffA);
;             PG8_BAR; PG8_WAIT_L(0); PG8_MMA(1, 0, At, B0); PG8_BAR; PG8_SCHED;
;             PG8_STAGE(PG8_SB(1, 1), b3 + hstep, voffB);
;             PG8_WAIT_V(6); PG8_BAR; PG8_MMA(1, 1, At, B1); PG8_BAR;
;         }
;         if (wr == 0) PG8_BAR;
	v_mfma_f32_16x16x32_bf16 v[66:69], v[238:241], v[222:225], v[66:69]
	s_setprio 0
	s_mov_b32 m0, s95
	v_lshl_add_u64 v[142:143], v[242:243], 0, s[12:13]
	ds_read_b128 v[194:197], v162 offset:49152
	ds_read_b128 v[198:201], v162 offset:50176
	ds_read_b128 v[202:205], v162 offset:51200
	ds_read_b128 v[206:209], v162 offset:52224
	ds_read_b128 v[210:213], v162 offset:53248
	ds_read_b128 v[214:217], v162 offset:54272
	ds_read_b128 v[218:221], v162 offset:55296
	ds_read_b128 v[222:225], v162 offset:56320
	global_load_lds_dwordx4 v[142:143], off
	v_lshl_add_u64 v[250:251], v[244:245], 0, s[12:13]
	s_mov_b32 m0, s96
	s_nop 0
	global_load_lds_dwordx4 v[250:251], off
	s_waitcnt vmcnt(8)
	s_barrier
	s_waitcnt lgkmcnt(0)
	s_setprio 1
	v_mfma_f32_16x16x32_bf16 v[62:65], v[164:167], v[194:197], v[62:65]
	v_mfma_f32_16x16x32_bf16 v[62:65], v[182:185], v[198:201], v[62:65]
	v_mfma_f32_16x16x32_bf16 v[58:61], v[186:189], v[194:197], v[58:61]
	v_mfma_f32_16x16x32_bf16 v[58:61], v[190:193], v[198:201], v[58:61]
	v_mfma_f32_16x16x32_bf16 v[54:57], v[164:167], v[202:205], v[54:57]
	v_mfma_f32_16x16x32_bf16 v[54:57], v[182:185], v[206:209], v[54:57]
	v_mfma_f32_16x16x32_bf16 v[46:49], v[186:189], v[202:205], v[46:49]
	v_mfma_f32_16x16x32_bf16 v[46:49], v[190:193], v[206:209], v[46:49]
	v_mfma_f32_16x16x32_bf16 v[38:41], v[164:167], v[210:213], v[38:41]
	v_mfma_f32_16x16x32_bf16 v[38:41], v[182:185], v[214:217], v[38:41]
	v_mfma_f32_16x16x32_bf16 v[30:33], v[186:189], v[210:213], v[30:33]
	v_mfma_f32_16x16x32_bf16 v[30:33], v[190:193], v[214:217], v[30:33]
	v_mfma_f32_16x16x32_bf16 v[22:25], v[164:167], v[218:221], v[22:25]
	v_mfma_f32_16x16x32_bf16 v[22:25], v[182:185], v[222:225], v[22:25]
	v_mfma_f32_16x16x32_bf16 v[14:17], v[186:189], v[218:221], v[14:17]
	s_barrier
	v_mfma_f32_16x16x32_bf16 v[14:17], v[190:193], v[222:225], v[14:17]
	s_setprio 0
	s_add_u32 s24, s48, 0x100080
	s_addc_u32 s25, s49, 0
	s_add_i32 s48, s76, s83
	v_lshl_add_u64 v[142:143], s[24:25], 0, v[134:135]
	s_mov_b32 m0, s48
	s_nop 0
	global_load_lds_dwordx4 v[142:143], off
	v_lshl_add_u64 v[250:251], s[24:25], 0, v[130:131]
	s_add_i32 m0, s48, 0x2000
	s_nop 0
	global_load_lds_dwordx4 v[250:251], off
	s_waitcnt vmcnt(6)
	v_add_u32_e32 v249, 0x10000, v144
	s_barrier
	s_setprio 1
	v_mfma_f32_16x16x32_bf16 v[50:53], v[226:229], v[194:197], v[50:53]
	ds_read_b128 v[164:167], v249
	ds_read_b128 v[182:185], v249 offset:1024
	v_mfma_f32_16x16x32_bf16 v[50:53], v[230:233], v[198:201], v[50:53]
	ds_read_b128 v[186:189], v249 offset:2048
	ds_read_b128 v[190:193], v249 offset:3072
	v_mfma_f32_16x16x32_bf16 v[42:45], v[234:237], v[194:197], v[42:45]
	ds_read_b128 v[194:197], v162
	v_mfma_f32_16x16x32_bf16 v[42:45], v[238:241], v[198:201], v[42:45]
	ds_read_b128 v[198:201], v162 offset:1024
	v_mfma_f32_16x16x32_bf16 v[34:37], v[226:229], v[202:205], v[34:37]
	v_mfma_f32_16x16x32_bf16 v[34:37], v[230:233], v[206:209], v[34:37]
	v_mfma_f32_16x16x32_bf16 v[26:29], v[234:237], v[202:205], v[26:29]
	ds_read_b128 v[202:205], v162 offset:2048
	v_mfma_f32_16x16x32_bf16 v[26:29], v[238:241], v[206:209], v[26:29]
	ds_read_b128 v[206:209], v162 offset:3072
	v_mfma_f32_16x16x32_bf16 v[18:21], v[226:229], v[210:213], v[18:21]
	v_mfma_f32_16x16x32_bf16 v[18:21], v[230:233], v[214:217], v[18:21]
	v_mfma_f32_16x16x32_bf16 v[10:13], v[234:237], v[210:213], v[10:13]
	ds_read_b128 v[210:213], v162 offset:4096
	v_mfma_f32_16x16x32_bf16 v[10:13], v[238:241], v[214:217], v[10:13]
	ds_read_b128 v[214:217], v162 offset:5120
	v_mfma_f32_16x16x32_bf16 v[6:9], v[226:229], v[218:221], v[6:9]
	v_mfma_f32_16x16x32_bf16 v[6:9], v[230:233], v[222:225], v[6:9]
	v_mfma_f32_16x16x32_bf16 v[2:5], v[234:237], v[218:221], v[2:5]
	s_barrier
	v_mfma_f32_16x16x32_bf16 v[2:5], v[238:241], v[222:225], v[2:5]
	s_setprio 0
	s_add_i32 s98, s98, 2
	s_add_u32 s35, s35, 0x100
	s_addc_u32 s50, s50, 0
	s_add_u32 s0, s0, 0x100
	s_addc_u32 s1, s1, 0
	s_cmp_gt_u32 s98, 61
	s_cbranch_scc0 .LBB0_627
	s_waitcnt lgkmcnt(0)
	s_and_b64 vcc, exec, s[40:41]
	s_cbranch_vccz .LBB0_630
	s_barrier
